# layer-2 decode attention loops: second-half latent rows requested at iteration top into spare VGPRs, next-iteration prefetch made unconditional (clamped on last iteration), all vmcnt recomputed from d
# baseline (speedup 1.0000x reference)
.LBB0_2268:
	s_lshl_b32 s17, s14, 5
	s_lshl_b32 s15, s16, 6
	s_and_b32 s17, s17, 32
	s_or_b32 s15, s15, s17
	s_lshl_b32 s17, s1, 2
	s_add_i32 s20, s15, s17
	s_lshl_b32 s2, s1, 14
	s_ashr_i32 s21, s20, 31
	s_add_i32 s10, s2, 0
	s_ashr_i32 s2, s1, 31
	s_lshl_b64 s[20:21], s[20:21], 2
	s_waitcnt lgkmcnt(0)
	s_add_u32 s18, s18, s20
	s_addc_u32 s19, s19, s21
	global_load_dwordx4 v[4:7], v1, s[18:19]
	v_mov_b32_e32 v3, v1
	s_barrier
	v_lshlrev_b32_e32 v0, 3, v36
	v_lshlrev_b32_e32 v38, 2, v36
	v_and_b32_e32 v36, 0x1f0, v0
	v_add_u32_e32 v41, s10, v36
	v_xad_u32 v42, v36, 32, s10
	v_xad_u32 v43, v36, 64, s10
	v_lshrrev_b32_e32 v37, 2, v155
	v_and_b32_e32 v40, 8, v0
	v_lshl_add_u32 v46, v155, 9, s10
	v_xor_b32_e32 v163, 64, v38
	v_xor_b32_e32 v164, 0x80, v38
	v_add_u32_e32 v182, v41, v40
	v_add_u32_e32 v183, v42, v40
	v_add_u32_e32 v184, v43, v40
	s_mov_b32 s15, 4
	s_mov_b32 s17, 0
	v_mov_b32_e32 v165, 0
	v_mov_b32_e32 v154, 0xf149f2ca
	s_movk_i32 s38, 0x2000
	s_waitcnt vmcnt(0)
	v_readfirstlane_b32 s24, v5
	v_readfirstlane_b32 s20, v4
	s_ashr_i32 s21, s20, 31
	s_ashr_i32 s25, s24, 31
	s_lshl_b64 s[22:23], s[24:25], 17
	s_lshl_b64 s[18:19], s[20:21], 17
	s_add_u32 s18, s4, s18
	s_addc_u32 s19, s5, s19
	v_lshl_add_u64 v[10:11], s[18:19], 0, v[2:3]
	v_add_co_u32_e32 v10, vcc, s96, v10
	v_readfirstlane_b32 s34, v7
	s_nop 0
	v_addc_co_u32_e32 v11, vcc, 0, v11, vcc
	v_readfirstlane_b32 s28, v6
	global_load_dwordx4 v[22:25], v2, s[18:19]
	global_load_dwordx4 v[14:17], v2, s[18:19] offset:1024
	global_load_dwordx4 v[6:9], v2, s[18:19] offset:2048
	s_nop 0
	global_load_dwordx4 v[2:5], v2, s[18:19] offset:3072
	s_nop 0
	global_load_dwordx4 v[30:33], v[10:11], off
	global_load_dwordx4 v[26:29], v[10:11], off offset:1024
	global_load_dwordx4 v[18:21], v[10:11], off offset:2048
	s_nop 0
	global_load_dwordx4 v[10:13], v[10:11], off offset:3072
	s_lshl_b64 s[20:21], s[20:21], 15
	s_add_u32 s20, s8, s20
	s_addc_u32 s21, s9, s21
	s_add_u32 s22, s4, s22
	s_addc_u32 s23, s5, s23
	s_lshl_b64 s[24:25], s[24:25], 15
	s_add_u32 s24, s8, s24
	s_addc_u32 s25, s9, s25
	s_ashr_i32 s29, s28, 31
	s_ashr_i32 s35, s34, 31
	s_lshl_b64 s[30:31], s[34:35], 17
	s_lshl_b64 s[26:27], s[28:29], 17
	s_add_u32 s26, s4, s26
	s_addc_u32 s27, s5, s27
	s_lshl_b64 s[28:29], s[28:29], 15
	s_add_u32 s28, s8, s28
	s_addc_u32 s29, s9, s29
	s_add_u32 s30, s4, s30
	s_addc_u32 s31, s5, s31
	s_lshl_b64 s[4:5], s[34:35], 15
	s_add_u32 s34, s8, s4
	s_movk_i32 s4, 0x60
	v_bitop3_b32 v36, v0, s4, v161 bitop3:0x6c
	s_movk_i32 s4, 0x80
	v_add_u32_e32 v44, s10, v36
	v_bitop3_b32 v36, v0, s4, v161 bitop3:0x6c
	s_movk_i32 s4, 0xa0
	v_add_u32_e32 v45, s10, v36
	v_bitop3_b32 v36, v0, s4, v161 bitop3:0x6c
	s_movk_i32 s4, 0xc0
	v_add_u32_e32 v47, s10, v36
	v_bitop3_b32 v36, v0, s4, v161 bitop3:0x6c
	s_movk_i32 s4, 0xe0
	v_add_u32_e32 v48, s10, v36
	v_bitop3_b32 v36, v0, s4, v161 bitop3:0x6c
	v_add_u32_e32 v49, s10, v36
	v_lshlrev_b32_e32 v36, 1, v155
	v_and_b32_e32 v50, 14, v36
	v_bitop3_b32 v36, v36, v35, 14 bitop3:0x6c
	v_lshlrev_b32_e32 v51, 4, v36
	v_bitop3_b32 v36, v35, v50, 4 bitop3:0x36
	v_lshlrev_b32_e32 v52, 4, v36
	v_bitop3_b32 v36, v35, v50, 8 bitop3:0x36
	v_lshlrev_b32_e32 v53, 4, v36
	v_bitop3_b32 v36, v35, v50, 12 bitop3:0x36
	v_lshlrev_b32_e32 v54, 4, v36
	v_bitop3_b32 v36, v35, v50, 16 bitop3:0x36
	v_lshlrev_b32_e32 v55, 4, v36
	v_bitop3_b32 v36, v35, v50, 20 bitop3:0x36
	v_lshlrev_b32_e32 v56, 4, v36
	v_bitop3_b32 v36, v35, v50, 24 bitop3:0x36
	v_lshlrev_b32_e32 v57, 4, v36
	v_bitop3_b32 v36, v35, v50, 28 bitop3:0x36
	v_lshlrev_b32_e32 v50, 4, v36
	v_lshl_or_b32 v35, v35, 2, v37
	v_bfe_u32 v36, v34, 1, 1
	v_lshlrev_b32_e32 v34, 3, v34
	v_and_b32_e32 v58, 8, v34
	v_lshlrev_b32_e32 v34, 1, v35
	v_and_b32_e32 v37, 14, v34
	v_or_b32_e32 v37, v37, v36
	v_lshl_add_u32 v35, v35, 9, s10
	v_lshl_add_u32 v59, v37, 4, v35
	v_or_b32_e32 v37, 2, v36
	v_bitop3_b32 v37, v34, v37, 14 bitop3:0x6c
	v_lshl_add_u32 v60, v37, 4, v35
	v_or_b32_e32 v37, 4, v36
	v_bitop3_b32 v37, v34, v37, 14 bitop3:0x6c
	v_lshl_add_u32 v61, v37, 4, v35
	v_or_b32_e32 v37, 6, v36
	v_bitop3_b32 v37, v34, v37, 14 bitop3:0x6c
	v_lshl_add_u32 v62, v37, 4, v35
	v_or_b32_e32 v37, 8, v36
	v_bitop3_b32 v37, v34, v37, 14 bitop3:0x6c
	v_lshl_add_u32 v63, v37, 4, v35
	v_or_b32_e32 v37, 10, v36
	v_bitop3_b32 v37, v34, v37, 14 bitop3:0x6c
	v_lshl_add_u32 v64, v37, 4, v35
	v_or_b32_e32 v37, 12, v36
	v_bitop3_b32 v37, v34, v37, 14 bitop3:0x6c
	v_lshl_add_u32 v65, v37, 4, v35
	v_bitop3_b32 v37, v34, v36, 14 bitop3:0x4e
	v_lshl_add_u32 v66, v37, 4, v35
	v_or_b32_e32 v37, v34, v36
	v_lshl_or_b32 v37, v37, 4, v162
	v_add_u32_e32 v67, v35, v37
	v_or_b32_e32 v37, 18, v36
	v_bitop3_b32 v37, v34, v37, 14 bitop3:0x6c
	v_lshl_add_u32 v68, v37, 4, v35
	v_or_b32_e32 v37, 20, v36
	v_bitop3_b32 v37, v34, v37, 14 bitop3:0x6c
	v_lshl_add_u32 v69, v37, 4, v35
	v_or_b32_e32 v37, 22, v36
	s_addc_u32 s35, s9, s5
	v_bitop3_b32 v37, v34, v37, 14 bitop3:0x6c
	v_lshl_add_u32 v70, v37, 4, v35
	v_or_b32_e32 v37, 24, v36
	s_add_u32 s1, s12, s1
	v_bitop3_b32 v37, v34, v37, 14 bitop3:0x6c
	s_addc_u32 s2, s13, s2
	v_lshl_add_u32 v71, v37, 4, v35
	v_or_b32_e32 v37, 26, v36
	s_mul_i32 s2, s2, 0x28000
	s_mul_hi_u32 s4, s1, 0x28000
	v_bitop3_b32 v37, v34, v37, 14 bitop3:0x6c
	s_add_i32 s2, s4, s2
	s_mul_i32 s1, s1, 0x28000
	v_lshl_add_u32 v72, v37, 4, v35
	v_or_b32_e32 v37, 28, v36
	v_or_b32_e32 v36, 30, v36
	s_add_u32 s4, s75, s1
	v_bitop3_b32 v37, v34, v37, 14 bitop3:0x6c
	v_bitop3_b32 v34, v34, v36, 14 bitop3:0x6c
	s_addc_u32 s5, s76, s2
	v_lshl_add_u32 v73, v37, 4, v35
	v_lshl_add_u32 v74, v34, 4, v35
	v_lshl_add_u64 v[152:153], s[4:5], 0, v[0:1]
	v_mov_b32_e32 v36, v1
	v_mov_b32_e32 v37, v1
	v_lshlrev_b32_e32 v0, 2, v38
	v_add_u32_e32 v38, 0, v39
	v_mov_b32_e32 v34, v1
	v_mov_b32_e32 v35, v1
	v_add_u32_e32 v166, v59, v58
	v_add_u32_e32 v167, v60, v58
	v_add_u32_e32 v168, v61, v58
	v_add_u32_e32 v169, v62, v58
	v_add_u32_e32 v170, v63, v58
	v_add_u32_e32 v171, v64, v58
	v_add_u32_e32 v172, v65, v58
	v_add_u32_e32 v173, v66, v58
	v_add_u32_e32 v174, v67, v58
	v_add_u32_e32 v175, v68, v58
	v_add_u32_e32 v176, v69, v58
	v_add_u32_e32 v177, v70, v58
	v_add_u32_e32 v178, v71, v58
	v_add_u32_e32 v179, v72, v58
	v_add_u32_e32 v180, v73, v58
	v_add_u32_e32 v181, v74, v58
	v_add_u32_e32 v185, v44, v40
	v_add_u32_e32 v186, v45, v40
	v_add_u32_e32 v187, v47, v40
	v_add_u32_e32 v188, v48, v40
	v_add_u32_e32 v189, v49, v40
	v_add_u32_e32 v190, v46, v51
	v_add_u32_e32 v191, 0x21000, v38
	v_add_u32_e32 v192, v46, v52
	v_add_u32_e32 v193, v46, v53
	v_add_u32_e32 v194, v46, v54
	v_add_u32_e32 v195, v46, v55
	v_add_u32_e32 v196, v46, v56
	v_add_u32_e32 v197, v46, v57
	v_add_u32_e32 v198, v46, v50
	v_mov_b64_e32 v[96:97], v[36:37]
	v_mov_b64_e32 v[92:93], v[36:37]
	v_mov_b64_e32 v[88:89], v[36:37]
	v_mov_b64_e32 v[84:85], v[36:37]
	v_mov_b64_e32 v[80:81], v[36:37]
	v_mov_b64_e32 v[76:77], v[36:37]
	v_mov_b64_e32 v[72:73], v[36:37]
	v_mov_b64_e32 v[68:69], v[36:37]
	v_mov_b64_e32 v[64:65], v[36:37]
	v_mov_b64_e32 v[60:61], v[36:37]
	v_mov_b64_e32 v[56:57], v[36:37]
	v_mov_b64_e32 v[52:53], v[36:37]
	v_mov_b64_e32 v[48:49], v[36:37]
	v_mov_b64_e32 v[44:45], v[36:37]
	v_mov_b64_e32 v[40:41], v[36:37]
	v_mov_b64_e32 v[94:95], v[34:35]
	v_mov_b64_e32 v[90:91], v[34:35]
	v_mov_b64_e32 v[86:87], v[34:35]
	v_mov_b64_e32 v[82:83], v[34:35]
	v_mov_b64_e32 v[78:79], v[34:35]
	v_mov_b64_e32 v[74:75], v[34:35]
	v_mov_b64_e32 v[70:71], v[34:35]
	v_mov_b64_e32 v[66:67], v[34:35]
	v_mov_b64_e32 v[62:63], v[34:35]
	v_mov_b64_e32 v[58:59], v[34:35]
	v_mov_b64_e32 v[54:55], v[34:35]
	v_mov_b64_e32 v[50:51], v[34:35]
	v_mov_b64_e32 v[46:47], v[34:35]
	v_mov_b64_e32 v[42:43], v[34:35]
	v_mov_b64_e32 v[38:39], v[34:35]
	s_waitcnt vmcnt(0)
	s_branch .LBB0_2270

.LBB0_2279:
	s_and_b32 s2, s17, 0x60
	s_lshl_b32 s8, s2, 10
	s_add_u32 s8, s36, s8
	s_addc_u32 s9, s37, 0
	v_lshl_add_u64 v[98:99], s[8:9], 0, v[0:1]
	v_add_co_u32_e32 v102, vcc, 0x2000, v98
	v_lshl_add_u64 v[100:101], v[98:99], 0, s[64:65]
	s_nop 0
	v_addc_co_u32_e32 v103, vcc, 0, v99, vcc
	v_add_co_u32_e32 v98, vcc, 0x3000, v98
	global_load_dwordx4 v[138:141], v[100:101], off offset:1024
	global_load_dwordx4 v[134:137], v[100:101], off offset:2048
	global_load_dwordx4 v[142:145], v[102:103], off
	global_load_dwordx4 v[130:133], v[100:101], off offset:3072
	v_addc_co_u32_e32 v99, vcc, 0, v99, vcc
	global_load_dwordx4 v[126:129], v[98:99], off
	global_load_dwordx4 v[122:125], v[98:99], off offset:1024
	global_load_dwordx4 v[118:121], v[98:99], off offset:2048
	global_load_dwordx4 v[114:117], v[98:99], off offset:3072
	s_mov_b64 s[46:47], 0x4000
	v_lshl_add_u64 v[250:251], v[100:101], 0, s[46:47]
	v_lshl_add_u64 v[252:253], v[98:99], 0, s[46:47]
	global_load_dwordx4 v[202:205], v[250:251], off offset:1024
	global_load_dwordx4 v[206:209], v[250:251], off offset:2048
	global_load_dwordx4 v[210:213], v[250:251], off
	global_load_dwordx4 v[214:217], v[250:251], off offset:3072
	global_load_dwordx4 v[218:221], v[252:253], off
	global_load_dwordx4 v[222:225], v[252:253], off offset:1024
	global_load_dwordx4 v[226:229], v[252:253], off offset:2048
	global_load_dwordx4 v[230:233], v[252:253], off offset:3072
	v_cndmask_b32_e64 v98, 0, 1, s[4:5]
	v_cmp_ne_u32_e64 s[8:9], 1, v98
	s_andn2_b64 vcc, exec, s[4:5]
	s_mov_b64 s[36:37], s[20:21]
	s_cbranch_vccnz .LBB0_2288
	s_cmp_lt_i32 s1, 2
	s_cbranch_scc1 .LBB0_2284
	s_cmp_eq_u32 s1, 2
	s_mov_b64 s[4:5], -1
	s_cbranch_scc0 .LBB0_2283
	s_mov_b64 s[4:5], 0

.LBB0_2288:
	v_or_b32_e32 v98, s2, v155
	v_lshlrev_b32_e32 v98, 8, v98
	v_mov_b32_e32 v99, v1
	v_lshl_add_u64 v[98:99], s[36:37], 0, v[98:99]
	v_lshl_add_u64 v[98:99], v[150:151], 2, v[98:99]
	global_load_dwordx4 v[110:113], v[98:99], off offset:16
	global_load_dwordx4 v[106:109], v[98:99], off
	global_load_dwordx4 v[102:105], v[98:99], off offset:144
	s_nop 0
	global_load_dwordx4 v[98:101], v[98:99], off offset:128
	s_waitcnt vmcnt(37)
	v_cvt_pk_bf16_f32 v22, v22, v23
	v_cvt_pk_bf16_f32 v23, v24, v25
	ds_write_b64 v182, v[22:23]
	s_waitcnt vmcnt(36)
	v_cvt_pk_bf16_f32 v14, v14, v15
	v_cvt_pk_bf16_f32 v15, v16, v17
	ds_write_b64 v183, v[14:15] offset:512
	s_waitcnt vmcnt(35)
	v_cvt_pk_bf16_f32 v6, v6, v7
	v_cvt_pk_bf16_f32 v7, v8, v9
	ds_write_b64 v184, v[6:7] offset:1024
	s_waitcnt vmcnt(34)
	v_cvt_pk_bf16_f32 v2, v2, v3
	v_cvt_pk_bf16_f32 v3, v4, v5
	ds_write_b64 v185, v[2:3] offset:1536
	s_waitcnt vmcnt(33)
	v_cvt_pk_bf16_f32 v2, v30, v31
	v_cvt_pk_bf16_f32 v3, v32, v33
	ds_write_b64 v186, v[2:3] offset:2048
	s_waitcnt vmcnt(32)
	v_cvt_pk_bf16_f32 v2, v26, v27
	v_cvt_pk_bf16_f32 v3, v28, v29
	ds_write_b64 v187, v[2:3] offset:2560
	s_waitcnt vmcnt(31)
	v_cvt_pk_bf16_f32 v2, v18, v19
	v_cvt_pk_bf16_f32 v3, v20, v21
	ds_write_b64 v188, v[2:3] offset:3072
	s_waitcnt vmcnt(30)
	v_cvt_pk_bf16_f32 v2, v10, v11
	v_cvt_pk_bf16_f32 v3, v12, v13
	ds_write_b64 v189, v[2:3] offset:3584
	s_and_b64 vcc, exec, s[8:9]
	s_mov_b64 s[4:5], s[18:19]
	s_cbranch_vccnz .LBB0_2297
	s_cmp_lt_i32 s1, 2
	s_cbranch_scc1 .LBB0_2293
	s_cmp_eq_u32 s1, 2
	s_mov_b64 s[36:37], -1
	s_cbranch_scc0 .LBB0_2292
	s_mov_b64 s[36:37], 0

.LBB0_2297:
	s_add_i32 s10, s38, 0xffffe000
	s_and_b32 s10, s10, 0x6000
	s_lshl_b32 s10, s10, 2
	s_add_u32 s4, s4, s10
	s_addc_u32 s5, s5, 0
	v_lshl_add_u64 v[2:3], s[4:5], 0, v[0:1]
	s_mov_b64 s[4:5], 0x4000
	v_lshl_add_u64 v[4:5], v[2:3], 0, s[4:5]
	s_movk_i32 s4, 0x5000
	v_add_co_u32_e32 v10, vcc, s4, v2
	s_nop 1
	v_addc_co_u32_e32 v11, vcc, 0, v3, vcc
	global_load_dwordx4 v[14:17], v[4:5], off offset:1024
	global_load_dwordx4 v[6:9], v[4:5], off offset:2048
	global_load_dwordx4 v[22:25], v[10:11], off offset:-4096
	s_nop 0
	global_load_dwordx4 v[2:5], v[4:5], off offset:3072
	s_nop 0
	global_load_dwordx4 v[30:33], v[10:11], off
	global_load_dwordx4 v[26:29], v[10:11], off offset:1024
	global_load_dwordx4 v[18:21], v[10:11], off offset:2048
	s_nop 0
	global_load_dwordx4 v[10:13], v[10:11], off offset:3072
	s_waitcnt vmcnt(25)
	v_cvt_pk_bf16_f32 v142, v142, v143
	v_cvt_pk_bf16_f32 v143, v144, v145
	ds_write_b64 v182, v[142:143] offset:4096
	v_cvt_pk_bf16_f32 v138, v138, v139
	v_cvt_pk_bf16_f32 v139, v140, v141
	ds_write_b64 v183, v[138:139] offset:4608
	v_cvt_pk_bf16_f32 v134, v134, v135
	v_cvt_pk_bf16_f32 v135, v136, v137
	ds_write_b64 v184, v[134:135] offset:5120
	s_waitcnt vmcnt(24)
	v_cvt_pk_bf16_f32 v130, v130, v131
	v_cvt_pk_bf16_f32 v131, v132, v133
	ds_write_b64 v185, v[130:131] offset:5632
	s_waitcnt vmcnt(23)
	v_cvt_pk_bf16_f32 v126, v126, v127
	v_cvt_pk_bf16_f32 v127, v128, v129
	ds_write_b64 v186, v[126:127] offset:6144
	s_waitcnt vmcnt(22)
	v_cvt_pk_bf16_f32 v122, v122, v123
	v_cvt_pk_bf16_f32 v123, v124, v125
	ds_write_b64 v187, v[122:123] offset:6656
	s_waitcnt vmcnt(21)
	v_cvt_pk_bf16_f32 v118, v118, v119
	v_cvt_pk_bf16_f32 v119, v120, v121
	ds_write_b64 v188, v[118:119] offset:7168
	s_waitcnt vmcnt(20)
	v_cvt_pk_bf16_f32 v114, v114, v115
	v_cvt_pk_bf16_f32 v115, v116, v117
	ds_write_b64 v189, v[114:115] offset:7680
	ds_read_b128 v[114:117], v190
	v_mov_b32_e32 v119, v1
	s_waitcnt lgkmcnt(0)
	v_lshlrev_b32_e32 v121, 16, v116
	v_and_b32_e32 v122, 0xffff0000, v116
	v_cvt_pk_fp8_f32 v119, v121, v122
	v_lshlrev_b32_e32 v118, 16, v117
	v_and_b32_e32 v120, 0xffff0000, v117
	v_lshlrev_b32_e32 v122, 16, v114
	v_cvt_pk_fp8_f32 v119, v118, v120 op_sel:[0,0,1]
	v_and_b32_e32 v123, 0xffff0000, v114
	v_mov_b32_e32 v118, v1
	v_cvt_pk_fp8_f32 v118, v122, v123
	v_lshlrev_b32_e32 v120, 16, v115
	v_and_b32_e32 v121, 0xffff0000, v115
	v_mov_b32_e32 v123, v1
	v_cvt_pk_fp8_f32 v118, v120, v121 op_sel:[0,0,1]
	global_store_dwordx2 v[152:153], v[118:119], off
	ds_read_b128 v[118:121], v191
	s_waitcnt lgkmcnt(0)
	v_mfma_f32_16x16x32_bf16 v[114:117], v[114:117], v[118:121], 0
	ds_read_b128 v[118:121], v192
	s_waitcnt lgkmcnt(0)
	v_lshlrev_b32_e32 v125, 16, v120
	v_and_b32_e32 v126, 0xffff0000, v120
	v_cvt_pk_fp8_f32 v123, v125, v126
	v_lshlrev_b32_e32 v122, 16, v121
	v_and_b32_e32 v124, 0xffff0000, v121
	v_lshlrev_b32_e32 v126, 16, v118
	v_cvt_pk_fp8_f32 v123, v122, v124 op_sel:[0,0,1]
	v_and_b32_e32 v127, 0xffff0000, v118
	v_mov_b32_e32 v122, v1
	v_cvt_pk_fp8_f32 v122, v126, v127
	v_lshlrev_b32_e32 v124, 16, v119
	v_and_b32_e32 v125, 0xffff0000, v119
	v_cvt_pk_fp8_f32 v122, v124, v125 op_sel:[0,0,1]
	global_store_dwordx2 v[152:153], v[122:123], off offset:512
	ds_read_b128 v[122:125], v191 offset:1024
	s_waitcnt lgkmcnt(0)
	v_mfma_f32_16x16x32_bf16 v[114:117], v[118:121], v[122:125], v[114:117]
	ds_read_b128 v[118:121], v193
	v_mov_b32_e32 v123, v1
	s_waitcnt lgkmcnt(0)
	v_lshlrev_b32_e32 v125, 16, v120
	v_and_b32_e32 v126, 0xffff0000, v120
	v_cvt_pk_fp8_f32 v123, v125, v126
	v_lshlrev_b32_e32 v122, 16, v121
	v_and_b32_e32 v124, 0xffff0000, v121
	v_lshlrev_b32_e32 v126, 16, v118
	v_cvt_pk_fp8_f32 v123, v122, v124 op_sel:[0,0,1]
	v_and_b32_e32 v127, 0xffff0000, v118
	v_mov_b32_e32 v122, v1
	v_cvt_pk_fp8_f32 v122, v126, v127
	v_lshlrev_b32_e32 v124, 16, v119
	v_and_b32_e32 v125, 0xffff0000, v119
	v_cvt_pk_fp8_f32 v122, v124, v125 op_sel:[0,0,1]
	global_store_dwordx2 v[152:153], v[122:123], off offset:1024
	ds_read_b128 v[122:125], v191 offset:2048
	s_waitcnt lgkmcnt(0)
	v_mfma_f32_16x16x32_bf16 v[114:117], v[118:121], v[122:125], v[114:117]
	ds_read_b128 v[118:121], v194
	v_mov_b32_e32 v123, v1
	s_waitcnt lgkmcnt(0)
	v_lshlrev_b32_e32 v125, 16, v120
	v_and_b32_e32 v126, 0xffff0000, v120
	v_cvt_pk_fp8_f32 v123, v125, v126
	v_lshlrev_b32_e32 v122, 16, v121
	v_and_b32_e32 v124, 0xffff0000, v121
	v_lshlrev_b32_e32 v126, 16, v118
	v_cvt_pk_fp8_f32 v123, v122, v124 op_sel:[0,0,1]
	v_and_b32_e32 v127, 0xffff0000, v118
	v_mov_b32_e32 v122, v1
	v_cvt_pk_fp8_f32 v122, v126, v127
	v_lshlrev_b32_e32 v124, 16, v119
	v_and_b32_e32 v125, 0xffff0000, v119
	v_cvt_pk_fp8_f32 v122, v124, v125 op_sel:[0,0,1]
	global_store_dwordx2 v[152:153], v[122:123], off offset:1536
	ds_read_b128 v[122:125], v191 offset:3072
	s_waitcnt lgkmcnt(0)
	v_mfma_f32_16x16x32_bf16 v[114:117], v[118:121], v[122:125], v[114:117]
	ds_read_b128 v[118:121], v195
	v_mov_b32_e32 v123, v1
	s_waitcnt lgkmcnt(0)
	v_lshlrev_b32_e32 v125, 16, v120
	v_and_b32_e32 v126, 0xffff0000, v120
	v_cvt_pk_fp8_f32 v123, v125, v126
	v_lshlrev_b32_e32 v122, 16, v121
	v_and_b32_e32 v124, 0xffff0000, v121
	v_lshlrev_b32_e32 v126, 16, v118
	v_cvt_pk_fp8_f32 v123, v122, v124 op_sel:[0,0,1]
	v_and_b32_e32 v127, 0xffff0000, v118
	v_mov_b32_e32 v122, v1
	v_cvt_pk_fp8_f32 v122, v126, v127
	v_lshlrev_b32_e32 v124, 16, v119
	v_and_b32_e32 v125, 0xffff0000, v119
	v_cvt_pk_fp8_f32 v122, v124, v125 op_sel:[0,0,1]
	global_store_dwordx2 v[152:153], v[122:123], off offset:2048
	ds_read_b128 v[122:125], v191 offset:4096
	s_waitcnt lgkmcnt(0)
	v_mfma_f32_16x16x32_bf16 v[114:117], v[118:121], v[122:125], v[114:117]
	ds_read_b128 v[118:121], v196
	v_mov_b32_e32 v123, v1
	s_waitcnt lgkmcnt(0)
	v_lshlrev_b32_e32 v125, 16, v120
	v_and_b32_e32 v126, 0xffff0000, v120
	v_cvt_pk_fp8_f32 v123, v125, v126
	v_lshlrev_b32_e32 v122, 16, v121
	v_and_b32_e32 v124, 0xffff0000, v121
	v_lshlrev_b32_e32 v126, 16, v118
	v_cvt_pk_fp8_f32 v123, v122, v124 op_sel:[0,0,1]
	v_and_b32_e32 v127, 0xffff0000, v118
	v_mov_b32_e32 v122, v1
	v_cvt_pk_fp8_f32 v122, v126, v127
	v_lshlrev_b32_e32 v124, 16, v119
	v_and_b32_e32 v125, 0xffff0000, v119
	v_cvt_pk_fp8_f32 v122, v124, v125 op_sel:[0,0,1]
	global_store_dwordx2 v[152:153], v[122:123], off offset:2560
	ds_read_b128 v[122:125], v191 offset:5120
	s_waitcnt lgkmcnt(0)
	v_mfma_f32_16x16x32_bf16 v[114:117], v[118:121], v[122:125], v[114:117]
	ds_read_b128 v[118:121], v197
	v_mov_b32_e32 v123, v1
	s_waitcnt lgkmcnt(0)
	v_lshlrev_b32_e32 v125, 16, v120
	v_and_b32_e32 v126, 0xffff0000, v120
	v_cvt_pk_fp8_f32 v123, v125, v126
	v_lshlrev_b32_e32 v122, 16, v121
	v_and_b32_e32 v124, 0xffff0000, v121
	v_lshlrev_b32_e32 v126, 16, v118
	v_cvt_pk_fp8_f32 v123, v122, v124 op_sel:[0,0,1]
	v_and_b32_e32 v127, 0xffff0000, v118
	v_mov_b32_e32 v122, v1
	v_cvt_pk_fp8_f32 v122, v126, v127
	v_lshlrev_b32_e32 v124, 16, v119
	v_and_b32_e32 v125, 0xffff0000, v119
	v_cvt_pk_fp8_f32 v122, v124, v125 op_sel:[0,0,1]
	global_store_dwordx2 v[152:153], v[122:123], off offset:3072
	ds_read_b128 v[122:125], v191 offset:6144
	s_waitcnt lgkmcnt(0)
	v_mfma_f32_16x16x32_bf16 v[114:117], v[118:121], v[122:125], v[114:117]
	ds_read_b128 v[118:121], v198
	v_mov_b32_e32 v123, v1
	s_waitcnt lgkmcnt(0)
	v_lshlrev_b32_e32 v125, 16, v120
	v_and_b32_e32 v126, 0xffff0000, v120
	v_cvt_pk_fp8_f32 v123, v125, v126
	v_lshlrev_b32_e32 v122, 16, v121
	v_and_b32_e32 v124, 0xffff0000, v121
	v_lshlrev_b32_e32 v126, 16, v118
	v_cvt_pk_fp8_f32 v123, v122, v124 op_sel:[0,0,1]
	v_and_b32_e32 v127, 0xffff0000, v118
	v_mov_b32_e32 v122, v1
	v_cvt_pk_fp8_f32 v122, v126, v127
	v_lshlrev_b32_e32 v124, 16, v119
	v_and_b32_e32 v125, 0xffff0000, v119
	v_cvt_pk_fp8_f32 v122, v124, v125 op_sel:[0,0,1]
	global_store_dwordx2 v[152:153], v[122:123], off offset:3584
	ds_read_b128 v[122:125], v191 offset:7168
	s_waitcnt lgkmcnt(0)
	v_mfma_f32_16x16x32_bf16 v[114:117], v[118:121], v[122:125], v[114:117]
	v_mov_b32_e32 v122, v1
	s_waitcnt vmcnt(18)
	v_cvt_pk_fp8_f32 v122, v106, v107
	v_cvt_pk_bf16_f32 v118, v106, v107
	v_cvt_pk_bf16_f32 v119, v108, v109
	v_cvt_pk_bf16_f32 v120, v110, v111
	v_cvt_pk_bf16_f32 v121, v112, v113
	v_cvt_pk_fp8_f32 v122, v108, v109 op_sel:[0,0,1]
	ds_read_b128 v[106:109], v191 offset:8192
	v_mov_b32_e32 v123, v1
	v_cvt_pk_fp8_f32 v123, v110, v111
	s_waitcnt lgkmcnt(0)
	v_mfma_f32_16x16x32_bf16 v[106:109], v[118:121], v[106:109], v[114:117]
	v_cvt_pk_fp8_f32 v123, v112, v113 op_sel:[0,0,1]
	s_nop 1
	v_mov_b32_e32 v114, v1
	s_waitcnt vmcnt(16)
	v_cvt_pk_fp8_f32 v114, v98, v99
	v_add_co_u32_e32 v156, vcc, s96, v152
	v_mov_b32_e32 v115, v1
	s_nop 0
	v_addc_co_u32_e32 v157, vcc, 0, v153, vcc
	global_store_dwordx2 v[156:157], v[122:123], off
	v_cvt_pk_bf16_f32 v110, v98, v99
	v_cvt_pk_bf16_f32 v111, v100, v101
	v_cvt_pk_bf16_f32 v112, v102, v103
	v_cvt_pk_bf16_f32 v113, v104, v105
	v_cvt_pk_fp8_f32 v114, v100, v101 op_sel:[0,0,1]
	ds_read_b128 v[98:101], v191 offset:9216
	v_cvt_pk_fp8_f32 v115, v102, v103
	s_waitcnt lgkmcnt(0)
	v_mfma_f32_16x16x32_bf16 v[98:101], v[110:113], v[98:101], v[106:109]
	v_cvt_pk_fp8_f32 v115, v104, v105 op_sel:[0,0,1]
	global_store_dwordx2 v[156:157], v[114:115], off offset:512
	s_and_b64 vcc, exec, s[8:9]
	s_mov_b64 s[36:37], s[18:19]
	s_cbranch_vccnz .LBB0_2306
	s_cmp_lt_i32 s1, 2
	s_cbranch_scc1 .LBB0_2302
	s_cmp_eq_u32 s1, 2
	s_mov_b64 s[4:5], -1
	s_cbranch_scc0 .LBB0_2301
	s_mov_b64 s[4:5], 0

.LBB0_2306:
	s_or_b32 s2, s2, 16
	s_lshl_b32 s4, s2, 10
	s_add_u32 s4, s36, s4
	s_addc_u32 s5, s37, 0
	v_lshl_add_u64 v[102:103], s[4:5], 0, v[0:1]
	v_add_co_u32_e32 v106, vcc, 0x2000, v102
	v_lshl_add_u64 v[104:105], v[102:103], 0, s[64:65]
	s_nop 0
	v_addc_co_u32_e32 v107, vcc, 0, v103, vcc
	v_add_co_u32_e32 v102, vcc, 0x3000, v102
	v_addc_co_u32_e32 v103, vcc, 0, v103, vcc
	s_and_b64 vcc, exec, s[8:9]
	s_mov_b64 s[8:9], s[20:21]
	s_cbranch_vccnz .LBB0_2315
	s_cmp_lt_i32 s1, 2
	s_cbranch_scc1 .LBB0_2311
	s_cmp_eq_u32 s1, 2
	s_mov_b64 s[4:5], -1
	s_cbranch_scc0 .LBB0_2310
	s_mov_b64 s[4:5], 0

.LBB0_2315:
	v_or_b32_e32 v102, s2, v155
	v_lshlrev_b32_e32 v102, 8, v102
	v_mov_b32_e32 v103, v1
	v_lshl_add_u64 v[102:103], s[8:9], 0, v[102:103]
	v_lshl_add_u64 v[102:103], v[150:151], 2, v[102:103]
	global_load_dwordx4 v[114:117], v[102:103], off offset:16
	global_load_dwordx4 v[110:113], v[102:103], off
	global_load_dwordx4 v[106:109], v[102:103], off offset:144
	s_nop 0
	global_load_dwordx4 v[102:105], v[102:103], off offset:128
	s_waitcnt vmcnt(19)
	v_cvt_pk_bf16_f32 v200, v22, v23
	v_cvt_pk_bf16_f32 v201, v24, v25
	ds_write_b64 v182, v[200:201] offset:8192
	v_cvt_pk_bf16_f32 v200, v14, v15
	v_cvt_pk_bf16_f32 v201, v16, v17
	ds_write_b64 v183, v[200:201] offset:8704
	v_cvt_pk_bf16_f32 v200, v6, v7
	v_cvt_pk_bf16_f32 v201, v8, v9
	ds_write_b64 v184, v[200:201] offset:9216
	s_waitcnt vmcnt(18)
	v_cvt_pk_bf16_f32 v200, v2, v3
	v_cvt_pk_bf16_f32 v201, v4, v5
	ds_write_b64 v185, v[200:201] offset:9728
	s_waitcnt vmcnt(17)
	v_cvt_pk_bf16_f32 v200, v30, v31
	v_cvt_pk_bf16_f32 v201, v32, v33
	ds_write_b64 v186, v[200:201] offset:10240
	s_waitcnt vmcnt(16)
	v_cvt_pk_bf16_f32 v200, v26, v27
	v_cvt_pk_bf16_f32 v201, v28, v29
	ds_write_b64 v187, v[200:201] offset:10752
	s_waitcnt vmcnt(15)
	v_cvt_pk_bf16_f32 v200, v18, v19
	v_cvt_pk_bf16_f32 v201, v20, v21
	ds_write_b64 v188, v[200:201] offset:11264
	s_waitcnt vmcnt(14)
	v_cvt_pk_bf16_f32 v200, v10, v11
	v_cvt_pk_bf16_f32 v201, v12, v13
	ds_write_b64 v189, v[200:201] offset:11776
	s_cmp_gt_u32 s39, 59
	s_cbranch_scc1 .Lmy_a2A_stub
	s_cmp_lt_u32 s39, 12
	s_mov_b64 s[4:5], s[18:19]
	s_cbranch_scc1 .LBB0_2322
	s_lshr_b32 s1, s15, 4
	s_cmp_lt_i32 s1, 2
	s_mov_b64 s[4:5], s[22:23]
	s_cbranch_scc1 .LBB0_2322
	s_cmp_lg_u32 s1, 2
	s_mov_b64 s[4:5], -1
	s_cbranch_scc0 .LBB0_2320
	s_mov_b64 s[4:5], 0

.LBB0_2323:
	v_cvt_pk_bf16_f32 v210, v210, v211
	v_cvt_pk_bf16_f32 v211, v212, v213
	ds_write_b64 v182, v[210:211] offset:12288
	v_cvt_pk_bf16_f32 v202, v202, v203
	v_cvt_pk_bf16_f32 v203, v204, v205
	ds_write_b64 v183, v[202:203] offset:12800
	v_cvt_pk_bf16_f32 v206, v206, v207
	v_cvt_pk_bf16_f32 v207, v208, v209
	ds_write_b64 v184, v[206:207] offset:13312
	v_cvt_pk_bf16_f32 v214, v214, v215
	v_cvt_pk_bf16_f32 v215, v216, v217
	ds_write_b64 v185, v[214:215] offset:13824
	v_cvt_pk_bf16_f32 v218, v218, v219
	v_cvt_pk_bf16_f32 v219, v220, v221
	ds_write_b64 v186, v[218:219] offset:14336
	v_cvt_pk_bf16_f32 v222, v222, v223
	v_cvt_pk_bf16_f32 v223, v224, v225
	ds_write_b64 v187, v[222:223] offset:14848
	v_cvt_pk_bf16_f32 v226, v226, v227
	v_cvt_pk_bf16_f32 v227, v228, v229
	ds_write_b64 v188, v[226:227] offset:15360
	v_cvt_pk_bf16_f32 v230, v230, v231
	v_cvt_pk_bf16_f32 v231, v232, v233
	ds_write_b64 v189, v[230:231] offset:15872
	ds_read_b128 v[118:121], v190 offset:8192
	v_mov_b32_e32 v123, v1
	s_waitcnt lgkmcnt(0)
	v_lshlrev_b32_e32 v125, 16, v120
	v_and_b32_e32 v126, 0xffff0000, v120
	v_cvt_pk_fp8_f32 v123, v125, v126
	v_lshlrev_b32_e32 v122, 16, v121
	v_and_b32_e32 v124, 0xffff0000, v121
	v_lshlrev_b32_e32 v126, 16, v118
	v_cvt_pk_fp8_f32 v123, v122, v124 op_sel:[0,0,1]
	v_and_b32_e32 v127, 0xffff0000, v118
	v_mov_b32_e32 v122, v1
	v_cvt_pk_fp8_f32 v122, v126, v127
	v_lshlrev_b32_e32 v124, 16, v119
	v_and_b32_e32 v125, 0xffff0000, v119
	v_mov_b32_e32 v127, v1
	v_cvt_pk_fp8_f32 v122, v124, v125 op_sel:[0,0,1]
	global_store_dwordx2 v[156:157], v[122:123], off offset:1024
	ds_read_b128 v[122:125], v191
	s_waitcnt lgkmcnt(0)
	v_mfma_f32_16x16x32_bf16 v[118:121], v[118:121], v[122:125], 0
	ds_read_b128 v[122:125], v192 offset:8192
	s_waitcnt lgkmcnt(0)
	v_lshlrev_b32_e32 v129, 16, v124
	v_and_b32_e32 v130, 0xffff0000, v124
	v_cvt_pk_fp8_f32 v127, v129, v130
	v_lshlrev_b32_e32 v126, 16, v125
	v_and_b32_e32 v128, 0xffff0000, v125
	v_lshlrev_b32_e32 v130, 16, v122
	v_cvt_pk_fp8_f32 v127, v126, v128 op_sel:[0,0,1]
	v_and_b32_e32 v131, 0xffff0000, v122
	v_mov_b32_e32 v126, v1
	v_cvt_pk_fp8_f32 v126, v130, v131
	v_lshlrev_b32_e32 v128, 16, v123
	v_and_b32_e32 v129, 0xffff0000, v123
	v_cvt_pk_fp8_f32 v126, v128, v129 op_sel:[0,0,1]
	global_store_dwordx2 v[156:157], v[126:127], off offset:1536
	ds_read_b128 v[126:129], v191 offset:1024
	s_waitcnt lgkmcnt(0)
	v_mfma_f32_16x16x32_bf16 v[118:121], v[122:125], v[126:129], v[118:121]
	ds_read_b128 v[122:125], v193 offset:8192
	v_mov_b32_e32 v127, v1
	s_waitcnt lgkmcnt(0)
	v_lshlrev_b32_e32 v129, 16, v124
	v_and_b32_e32 v130, 0xffff0000, v124
	v_cvt_pk_fp8_f32 v127, v129, v130
	v_lshlrev_b32_e32 v126, 16, v125
	v_and_b32_e32 v128, 0xffff0000, v125
	v_lshlrev_b32_e32 v130, 16, v122
	v_cvt_pk_fp8_f32 v127, v126, v128 op_sel:[0,0,1]
	v_and_b32_e32 v131, 0xffff0000, v122
	v_mov_b32_e32 v126, v1
	v_cvt_pk_fp8_f32 v126, v130, v131
	v_lshlrev_b32_e32 v128, 16, v123
	v_and_b32_e32 v129, 0xffff0000, v123
	v_cvt_pk_fp8_f32 v126, v128, v129 op_sel:[0,0,1]
	global_store_dwordx2 v[156:157], v[126:127], off offset:2048
	ds_read_b128 v[126:129], v191 offset:2048
	s_waitcnt lgkmcnt(0)
	v_mfma_f32_16x16x32_bf16 v[118:121], v[122:125], v[126:129], v[118:121]
	ds_read_b128 v[122:125], v194 offset:8192
	v_mov_b32_e32 v127, v1
	s_waitcnt lgkmcnt(0)
	v_lshlrev_b32_e32 v129, 16, v124
	v_and_b32_e32 v130, 0xffff0000, v124
	v_cvt_pk_fp8_f32 v127, v129, v130
	v_lshlrev_b32_e32 v126, 16, v125
	v_and_b32_e32 v128, 0xffff0000, v125
	v_lshlrev_b32_e32 v130, 16, v122
	v_cvt_pk_fp8_f32 v127, v126, v128 op_sel:[0,0,1]
	v_and_b32_e32 v131, 0xffff0000, v122
	v_mov_b32_e32 v126, v1
	v_cvt_pk_fp8_f32 v126, v130, v131
	v_lshlrev_b32_e32 v128, 16, v123
	v_and_b32_e32 v129, 0xffff0000, v123
	v_cvt_pk_fp8_f32 v126, v128, v129 op_sel:[0,0,1]
	global_store_dwordx2 v[156:157], v[126:127], off offset:2560
	ds_read_b128 v[126:129], v191 offset:3072
	s_waitcnt lgkmcnt(0)
	v_mfma_f32_16x16x32_bf16 v[118:121], v[122:125], v[126:129], v[118:121]
	ds_read_b128 v[122:125], v195 offset:8192
	v_mov_b32_e32 v127, v1
	s_waitcnt lgkmcnt(0)
	v_lshlrev_b32_e32 v129, 16, v124
	v_and_b32_e32 v130, 0xffff0000, v124
	v_cvt_pk_fp8_f32 v127, v129, v130
	v_lshlrev_b32_e32 v126, 16, v125
	v_and_b32_e32 v128, 0xffff0000, v125
	v_lshlrev_b32_e32 v130, 16, v122
	v_cvt_pk_fp8_f32 v127, v126, v128 op_sel:[0,0,1]
	v_and_b32_e32 v131, 0xffff0000, v122
	v_mov_b32_e32 v126, v1
	v_cvt_pk_fp8_f32 v126, v130, v131
	v_lshlrev_b32_e32 v128, 16, v123
	v_and_b32_e32 v129, 0xffff0000, v123
	v_cvt_pk_fp8_f32 v126, v128, v129 op_sel:[0,0,1]
	global_store_dwordx2 v[156:157], v[126:127], off offset:3072
	ds_read_b128 v[126:129], v191 offset:4096
	s_waitcnt lgkmcnt(0)
	v_mfma_f32_16x16x32_bf16 v[118:121], v[122:125], v[126:129], v[118:121]
	ds_read_b128 v[122:125], v196 offset:8192
	v_mov_b32_e32 v127, v1
	s_waitcnt lgkmcnt(0)
	v_lshlrev_b32_e32 v129, 16, v124
	v_and_b32_e32 v130, 0xffff0000, v124
	v_cvt_pk_fp8_f32 v127, v129, v130
	v_lshlrev_b32_e32 v126, 16, v125
	v_and_b32_e32 v128, 0xffff0000, v125
	v_lshlrev_b32_e32 v130, 16, v122
	v_cvt_pk_fp8_f32 v127, v126, v128 op_sel:[0,0,1]
	v_and_b32_e32 v131, 0xffff0000, v122
	v_mov_b32_e32 v126, v1
	v_cvt_pk_fp8_f32 v126, v130, v131
	v_lshlrev_b32_e32 v128, 16, v123
	v_and_b32_e32 v129, 0xffff0000, v123
	v_cvt_pk_fp8_f32 v126, v128, v129 op_sel:[0,0,1]
	global_store_dwordx2 v[156:157], v[126:127], off offset:3584
	ds_read_b128 v[126:129], v191 offset:5120
	s_waitcnt lgkmcnt(0)
	v_mfma_f32_16x16x32_bf16 v[120:123], v[122:125], v[126:129], v[118:121]
	ds_read_b128 v[124:127], v197 offset:8192
	v_mov_b32_e32 v129, v1
	s_movk_i32 s1, 0x2000
	s_waitcnt lgkmcnt(0)
	v_lshlrev_b32_e32 v128, 16, v126
	v_and_b32_e32 v130, 0xffff0000, v126
	v_cvt_pk_fp8_f32 v129, v128, v130
	v_lshlrev_b32_e32 v130, 16, v124
	v_and_b32_e32 v131, 0xffff0000, v124
	v_mov_b32_e32 v128, v1
	v_cvt_pk_fp8_f32 v128, v130, v131
	v_lshlrev_b32_e32 v118, 16, v127
	v_and_b32_e32 v119, 0xffff0000, v127
	v_cvt_pk_fp8_f32 v129, v118, v119 op_sel:[0,0,1]
	v_lshlrev_b32_e32 v118, 16, v125
	v_and_b32_e32 v119, 0xffff0000, v125
	v_cvt_pk_fp8_f32 v128, v118, v119 op_sel:[0,0,1]
	v_add_co_u32_e32 v118, vcc, s1, v152
	s_nop 1
	v_addc_co_u32_e32 v119, vcc, 0, v153, vcc
	global_store_dwordx2 v[118:119], v[128:129], off
	ds_read_b128 v[128:131], v191 offset:6144
	s_waitcnt lgkmcnt(0)
	v_mfma_f32_16x16x32_bf16 v[120:123], v[124:127], v[128:131], v[120:123]
	ds_read_b128 v[124:127], v198 offset:8192
	v_mov_b32_e32 v129, v1
	s_waitcnt lgkmcnt(0)
	v_lshlrev_b32_e32 v131, 16, v126
	v_and_b32_e32 v132, 0xffff0000, v126
	v_cvt_pk_fp8_f32 v129, v131, v132
	v_lshlrev_b32_e32 v128, 16, v127
	v_and_b32_e32 v130, 0xffff0000, v127
	v_lshlrev_b32_e32 v132, 16, v124
	v_cvt_pk_fp8_f32 v129, v128, v130 op_sel:[0,0,1]
	v_and_b32_e32 v133, 0xffff0000, v124
	v_mov_b32_e32 v128, v1
	v_cvt_pk_fp8_f32 v128, v132, v133
	v_lshlrev_b32_e32 v130, 16, v125
	v_and_b32_e32 v131, 0xffff0000, v125
	v_cvt_pk_fp8_f32 v128, v130, v131 op_sel:[0,0,1]
	global_store_dwordx2 v[118:119], v[128:129], off offset:512
	ds_read_b128 v[128:131], v191 offset:7168
	s_waitcnt lgkmcnt(0)
	v_mfma_f32_16x16x32_bf16 v[120:123], v[124:127], v[128:131], v[120:123]
	v_mov_b32_e32 v128, v1
	s_waitcnt vmcnt(18)
	v_cvt_pk_fp8_f32 v128, v110, v111
	v_cvt_pk_bf16_f32 v124, v110, v111
	v_cvt_pk_bf16_f32 v125, v112, v113
	v_cvt_pk_bf16_f32 v126, v114, v115
	v_cvt_pk_bf16_f32 v127, v116, v117
	v_cvt_pk_fp8_f32 v128, v112, v113 op_sel:[0,0,1]
	ds_read_b128 v[110:113], v191 offset:8192
	v_mov_b32_e32 v129, v1
	v_cvt_pk_fp8_f32 v129, v114, v115
	s_waitcnt lgkmcnt(0)
	v_mfma_f32_16x16x32_bf16 v[110:113], v[124:127], v[110:113], v[120:123]
	v_cvt_pk_fp8_f32 v129, v116, v117 op_sel:[0,0,1]
	s_nop 1
	v_mov_b32_e32 v120, v1
	s_waitcnt vmcnt(16)
	v_cvt_pk_fp8_f32 v120, v102, v103
	v_mov_b32_e32 v121, v1
	global_store_dwordx2 v[118:119], v[128:129], off offset:1024
	v_cvt_pk_bf16_f32 v114, v102, v103
	v_cvt_pk_bf16_f32 v115, v104, v105
	v_cvt_pk_bf16_f32 v116, v106, v107
	v_cvt_pk_bf16_f32 v117, v108, v109
	v_cvt_pk_fp8_f32 v120, v104, v105 op_sel:[0,0,1]
	ds_read_b128 v[102:105], v191 offset:9216
	v_cvt_pk_fp8_f32 v121, v106, v107
	s_waitcnt lgkmcnt(0)
	v_mfma_f32_16x16x32_bf16 v[102:105], v[114:117], v[102:105], v[110:113]
	v_cvt_pk_fp8_f32 v121, v108, v109 op_sel:[0,0,1]
	global_store_dwordx2 v[118:119], v[120:121], off offset:1536
	v_max_f32_e32 v106, v99, v99
	v_max_f32_e32 v107, v98, v98
	v_max_f32_e32 v106, v107, v106
	v_max_f32_e32 v107, v101, v101
	v_max_f32_e32 v108, v100, v100
	v_max_f32_e32 v107, v108, v107
	v_max_f32_e32 v108, v105, v105
	v_max_f32_e32 v109, v104, v104
	v_max_f32_e32 v108, v109, v108
	v_max3_f32 v108, v102, v103, v108
	v_max3_f32 v106, v106, v107, v108
	ds_bpermute_b32 v107, v163, v106
	s_waitcnt lgkmcnt(0)
	v_max_f32_e32 v107, v107, v107
	v_max_f32_e32 v106, v106, v107
	ds_bpermute_b32 v107, v164, v106
	s_waitcnt lgkmcnt(0)
	v_max_f32_e32 v107, v107, v107
	v_max_f32_e32 v106, v106, v107
	v_add_f32_e32 v107, 0x41000000, v154
	v_cmp_gt_f32_e32 vcc, v106, v107
	s_cbranch_vccz .LBB0_2269
	v_max_f32_e32 v106, v106, v106
	v_max_f32_e32 v107, v154, v154
	v_max_f32_e32 v107, v107, v106
	v_sub_f32_e32 v106, v154, v107
	v_exp_f32_e32 v106, v106
	v_mov_b32_e32 v154, v107
	v_pk_mul_f32 v[36:37], v[36:37], v[106:107] op_sel_hi:[1,0]
	v_pk_mul_f32 v[34:35], v[34:35], v[106:107] op_sel_hi:[1,0]
	v_pk_mul_f32 v[96:97], v[96:97], v[106:107] op_sel_hi:[1,0]
	v_pk_mul_f32 v[94:95], v[94:95], v[106:107] op_sel_hi:[1,0]
	v_pk_mul_f32 v[92:93], v[92:93], v[106:107] op_sel_hi:[1,0]
	v_pk_mul_f32 v[90:91], v[90:91], v[106:107] op_sel_hi:[1,0]
	v_pk_mul_f32 v[88:89], v[88:89], v[106:107] op_sel_hi:[1,0]
	v_pk_mul_f32 v[86:87], v[86:87], v[106:107] op_sel_hi:[1,0]
	v_pk_mul_f32 v[84:85], v[84:85], v[106:107] op_sel_hi:[1,0]
	v_pk_mul_f32 v[82:83], v[82:83], v[106:107] op_sel_hi:[1,0]
	v_pk_mul_f32 v[80:81], v[80:81], v[106:107] op_sel_hi:[1,0]
	v_pk_mul_f32 v[78:79], v[78:79], v[106:107] op_sel_hi:[1,0]
	v_pk_mul_f32 v[76:77], v[76:77], v[106:107] op_sel_hi:[1,0]
	v_pk_mul_f32 v[74:75], v[74:75], v[106:107] op_sel_hi:[1,0]
	v_pk_mul_f32 v[72:73], v[72:73], v[106:107] op_sel_hi:[1,0]
	v_pk_mul_f32 v[70:71], v[70:71], v[106:107] op_sel_hi:[1,0]
	v_pk_mul_f32 v[68:69], v[68:69], v[106:107] op_sel_hi:[1,0]
	v_pk_mul_f32 v[66:67], v[66:67], v[106:107] op_sel_hi:[1,0]
	v_pk_mul_f32 v[64:65], v[64:65], v[106:107] op_sel_hi:[1,0]
	v_pk_mul_f32 v[62:63], v[62:63], v[106:107] op_sel_hi:[1,0]
	v_pk_mul_f32 v[60:61], v[60:61], v[106:107] op_sel_hi:[1,0]
	v_pk_mul_f32 v[58:59], v[58:59], v[106:107] op_sel_hi:[1,0]
	v_pk_mul_f32 v[56:57], v[56:57], v[106:107] op_sel_hi:[1,0]
	v_pk_mul_f32 v[54:55], v[54:55], v[106:107] op_sel_hi:[1,0]
	v_pk_mul_f32 v[52:53], v[52:53], v[106:107] op_sel_hi:[1,0]
	v_pk_mul_f32 v[50:51], v[50:51], v[106:107] op_sel_hi:[1,0]
	v_pk_mul_f32 v[48:49], v[48:49], v[106:107] op_sel_hi:[1,0]
	v_pk_mul_f32 v[46:47], v[46:47], v[106:107] op_sel_hi:[1,0]
	v_pk_mul_f32 v[44:45], v[44:45], v[106:107] op_sel_hi:[1,0]
	v_pk_mul_f32 v[42:43], v[42:43], v[106:107] op_sel_hi:[1,0]
	v_pk_mul_f32 v[40:41], v[40:41], v[106:107] op_sel_hi:[1,0]
	v_pk_mul_f32 v[38:39], v[38:39], v[106:107] op_sel_hi:[1,0]
	v_mul_f32_e32 v165, v165, v106
	s_branch .LBB0_2269
.Lmy_a2A_stub:
	s_mov_b64 s[4:5], s[30:31]
	s_branch .LBB0_2322
.LBB0_2325:
	s_waitcnt vmcnt(0)
	v_mov_b32_e32 v2, v1
	ds_bpermute_b32 v0, v163, v165
	s_nop 0
	v_mbcnt_lo_u32_b32 v2, -1, v2
	v_mbcnt_hi_u32_b32 v4, -1, v2
	v_add_u32_e32 v21, s33, v4
	s_waitcnt lgkmcnt(0)
	v_add_f32_e32 v2, v165, v0
	v_readfirstlane_b32 s17, v21
	s_ashr_i32 s1, s17, 6
	ds_bpermute_b32 v3, v164, v2
	s_lshl_b32 s2, s1, 14
	v_and_b32_e32 v25, 63, v21
	s_add_i32 s2, s2, 0
	s_waitcnt lgkmcnt(0)
	v_lshl_add_u32 v0, v25, 2, s2
	ds_write2st64_b32 v0, v34, v35 offset1:1
	ds_write2st64_b32 v0, v36, v37 offset0:2 offset1:3
	ds_write2st64_b32 v0, v94, v95 offset0:4 offset1:5
	ds_write2st64_b32 v0, v96, v97 offset0:6 offset1:7
	ds_write2st64_b32 v0, v90, v91 offset0:8 offset1:9
	ds_write2st64_b32 v0, v92, v93 offset0:10 offset1:11
	ds_write2st64_b32 v0, v86, v87 offset0:12 offset1:13
	ds_write2st64_b32 v0, v88, v89 offset0:14 offset1:15
	ds_write2st64_b32 v0, v82, v83 offset0:16 offset1:17
	ds_write2st64_b32 v0, v84, v85 offset0:18 offset1:19
	ds_write2st64_b32 v0, v78, v79 offset0:20 offset1:21
	ds_write2st64_b32 v0, v80, v81 offset0:22 offset1:23
	ds_write2st64_b32 v0, v74, v75 offset0:24 offset1:25
	ds_write2st64_b32 v0, v76, v77 offset0:26 offset1:27
	ds_write2st64_b32 v0, v70, v71 offset0:28 offset1:29
	ds_write2st64_b32 v0, v72, v73 offset0:30 offset1:31
	ds_write2st64_b32 v0, v66, v67 offset0:32 offset1:33
	ds_write2st64_b32 v0, v68, v69 offset0:34 offset1:35
	ds_write2st64_b32 v0, v62, v63 offset0:36 offset1:37
	ds_write2st64_b32 v0, v64, v65 offset0:38 offset1:39
	ds_write2st64_b32 v0, v58, v59 offset0:40 offset1:41
	ds_write2st64_b32 v0, v60, v61 offset0:42 offset1:43
	ds_write2st64_b32 v0, v54, v55 offset0:44 offset1:45
	ds_write2st64_b32 v0, v56, v57 offset0:46 offset1:47
	ds_write2st64_b32 v0, v50, v51 offset0:48 offset1:49
	ds_write2st64_b32 v0, v52, v53 offset0:50 offset1:51
	ds_write2st64_b32 v0, v46, v47 offset0:52 offset1:53
	ds_write2st64_b32 v0, v48, v49 offset0:54 offset1:55
	ds_write2st64_b32 v0, v42, v43 offset0:56 offset1:57
	ds_write2st64_b32 v0, v44, v45 offset0:58 offset1:59
	ds_write2st64_b32 v0, v38, v39 offset0:60 offset1:61
	ds_write2st64_b32 v0, v40, v41 offset0:62 offset1:63
	v_and_b32_e32 v0, 15, v21
	v_cmp_gt_u32_e32 vcc, 16, v25
	v_cmp_lt_u32_e64 s[8:9], 15, v25
	v_lshlrev_b32_e32 v30, 3, v0
	s_and_saveexec_b64 s[4:5], s[8:9]
	s_xor_b64 s[4:5], exec, s[4:5]
	v_lshlrev_b32_e32 v4, 3, v0
	s_andn2_saveexec_b64 s[4:5], s[4:5]
	s_cbranch_execz .LBB0_2329
	s_lshl_b32 s2, s1, 7
	s_add_i32 s2, s2, 0
	s_waitcnt lgkmcnt(14)
	v_add_f32_e32 v155, v2, v3
	v_add_u32_e32 v2, s2, v30
	v_add_u32_e32 v2, 0x20000, v2
	v_mov_b32_e32 v4, v30
	ds_write_b64 v2, v[154:155]

.LBB0_2498:
	s_lshl_b32 s14, s1, 2
	s_add_i32 s14, s55, s14
	s_lshl_b32 s2, s1, 14
	s_ashr_i32 s15, s14, 31
	s_add_i32 s2, s2, 0
	s_lshl_b64 s[14:15], s[14:15], 2
	s_waitcnt lgkmcnt(0)
	s_add_u32 s12, s12, s14
	s_addc_u32 s13, s13, s15
	global_load_dwordx4 v[4:7], v1, s[12:13]
	v_mov_b32_e32 v3, v1
	s_barrier
	v_lshlrev_b32_e32 v0, 3, v36
	v_lshlrev_b32_e32 v38, 2, v36
	v_and_b32_e32 v36, 0x1f0, v0
	v_add_u32_e32 v41, s2, v36
	v_xad_u32 v42, v36, 32, s2
	v_xad_u32 v43, v36, 64, s2
	v_lshrrev_b32_e32 v37, 2, v155
	v_lshl_add_u32 v46, v155, 9, s2
	v_and_b32_e32 v40, 8, v0
	v_xor_b32_e32 v165, 64, v38
	v_xor_b32_e32 v164, 0x80, v38
	v_add_u32_e32 v183, v41, v40
	v_add_u32_e32 v184, v42, v40
	v_add_u32_e32 v185, v43, v40
	s_mov_b32 s30, 4
	s_mov_b32 s31, 0
	v_mov_b32_e32 v166, 0
	v_mov_b32_e32 v154, 0xf149f2ca
	s_movk_i32 s34, 0x2000
	s_waitcnt vmcnt(0)
	v_readfirstlane_b32 s18, v5
	v_readfirstlane_b32 s14, v4
	s_ashr_i32 s15, s14, 31
	s_ashr_i32 s19, s18, 31
	s_lshl_b64 s[16:17], s[18:19], 17
	s_lshl_b64 s[12:13], s[14:15], 17
	s_add_u32 s12, s4, s12
	s_addc_u32 s13, s5, s13
	v_lshl_add_u64 v[10:11], s[12:13], 0, v[2:3]
	v_add_co_u32_e32 v10, vcc, s63, v10
	v_readfirstlane_b32 s26, v7
	s_nop 0
	v_addc_co_u32_e32 v11, vcc, 0, v11, vcc
	v_readfirstlane_b32 s22, v6
	global_load_dwordx4 v[22:25], v2, s[12:13]
	global_load_dwordx4 v[14:17], v2, s[12:13] offset:1024
	global_load_dwordx4 v[6:9], v2, s[12:13] offset:2048
	s_nop 0
	global_load_dwordx4 v[2:5], v2, s[12:13] offset:3072
	s_nop 0
	global_load_dwordx4 v[30:33], v[10:11], off
	global_load_dwordx4 v[26:29], v[10:11], off offset:1024
	global_load_dwordx4 v[18:21], v[10:11], off offset:2048
	s_nop 0
	global_load_dwordx4 v[10:13], v[10:11], off offset:3072
	s_lshl_b64 s[14:15], s[14:15], 15
	s_add_u32 s14, s8, s14
	s_addc_u32 s15, s9, s15
	s_add_u32 s16, s4, s16
	s_addc_u32 s17, s5, s17
	s_lshl_b64 s[18:19], s[18:19], 15
	s_add_u32 s18, s8, s18
	s_addc_u32 s19, s9, s19
	s_ashr_i32 s23, s22, 31
	s_ashr_i32 s27, s26, 31
	s_lshl_b64 s[24:25], s[26:27], 17
	s_lshl_b64 s[20:21], s[22:23], 17
	s_add_u32 s20, s4, s20
	s_addc_u32 s21, s5, s21
	s_lshl_b64 s[22:23], s[22:23], 15
	s_add_u32 s22, s8, s22
	s_addc_u32 s23, s9, s23
	s_add_u32 s24, s4, s24
	s_addc_u32 s25, s5, s25
	s_lshl_b64 s[4:5], s[26:27], 15
	s_add_u32 s26, s8, s4
	s_movk_i32 s4, 0x60
	v_bitop3_b32 v36, v0, s4, v162 bitop3:0x6c
	s_movk_i32 s4, 0x80
	v_add_u32_e32 v44, s2, v36
	v_bitop3_b32 v36, v0, s4, v162 bitop3:0x6c
	s_movk_i32 s4, 0xa0
	v_add_u32_e32 v45, s2, v36
	v_bitop3_b32 v36, v0, s4, v162 bitop3:0x6c
	s_movk_i32 s4, 0xc0
	v_add_u32_e32 v47, s2, v36
	v_bitop3_b32 v36, v0, s4, v162 bitop3:0x6c
	s_movk_i32 s4, 0xe0
	v_add_u32_e32 v48, s2, v36
	v_bitop3_b32 v36, v0, s4, v162 bitop3:0x6c
	v_add_u32_e32 v49, s2, v36
	v_lshlrev_b32_e32 v36, 1, v155
	v_and_b32_e32 v57, 14, v36
	v_bitop3_b32 v36, v36, v35, 14 bitop3:0x6c
	v_lshlrev_b32_e32 v51, 4, v36
	v_bitop3_b32 v36, v35, v57, 4 bitop3:0x36
	v_lshlrev_b32_e32 v50, 4, v36
	v_bitop3_b32 v36, v35, v57, 8 bitop3:0x36
	v_lshlrev_b32_e32 v52, 4, v36
	v_bitop3_b32 v36, v35, v57, 12 bitop3:0x36
	v_lshlrev_b32_e32 v53, 4, v36
	v_bitop3_b32 v36, v35, v57, 16 bitop3:0x36
	v_lshlrev_b32_e32 v54, 4, v36
	v_bitop3_b32 v36, v35, v57, 20 bitop3:0x36
	v_lshlrev_b32_e32 v55, 4, v36
	v_bitop3_b32 v36, v35, v57, 24 bitop3:0x36
	v_lshlrev_b32_e32 v56, 4, v36
	v_bitop3_b32 v36, v35, v57, 28 bitop3:0x36
	v_lshlrev_b32_e32 v57, 4, v36
	v_lshl_or_b32 v35, v35, 2, v37
	v_bfe_u32 v36, v34, 1, 1
	v_lshlrev_b32_e32 v34, 3, v34
	v_and_b32_e32 v58, 8, v34
	v_lshlrev_b32_e32 v34, 1, v35
	v_and_b32_e32 v37, 14, v34
	v_or_b32_e32 v37, v37, v36
	v_lshl_add_u32 v35, v35, 9, s2
	v_lshl_add_u32 v59, v37, 4, v35
	v_or_b32_e32 v37, 2, v36
	v_bitop3_b32 v37, v34, v37, 14 bitop3:0x6c
	v_lshl_add_u32 v60, v37, 4, v35
	v_or_b32_e32 v37, 4, v36
	v_bitop3_b32 v37, v34, v37, 14 bitop3:0x6c
	v_lshl_add_u32 v61, v37, 4, v35
	v_or_b32_e32 v37, 6, v36
	v_bitop3_b32 v37, v34, v37, 14 bitop3:0x6c
	v_lshl_add_u32 v62, v37, 4, v35
	v_or_b32_e32 v37, 8, v36
	v_bitop3_b32 v37, v34, v37, 14 bitop3:0x6c
	v_lshl_add_u32 v63, v37, 4, v35
	v_or_b32_e32 v37, 10, v36
	v_bitop3_b32 v37, v34, v37, 14 bitop3:0x6c
	v_lshl_add_u32 v64, v37, 4, v35
	v_or_b32_e32 v37, 12, v36
	v_bitop3_b32 v37, v34, v37, 14 bitop3:0x6c
	v_lshl_add_u32 v65, v37, 4, v35
	v_bitop3_b32 v37, v34, v36, 14 bitop3:0x4e
	v_lshl_add_u32 v66, v37, 4, v35
	v_or_b32_e32 v37, v34, v36
	v_lshl_or_b32 v37, v37, 4, v163
	v_add_u32_e32 v67, v35, v37
	v_or_b32_e32 v37, 18, v36
	v_bitop3_b32 v37, v34, v37, 14 bitop3:0x6c
	v_lshl_add_u32 v68, v37, 4, v35
	v_or_b32_e32 v37, 20, v36
	v_bitop3_b32 v37, v34, v37, 14 bitop3:0x6c
	v_lshl_add_u32 v69, v37, 4, v35
	v_or_b32_e32 v37, 22, v36
	v_bitop3_b32 v37, v34, v37, 14 bitop3:0x6c
	v_lshl_add_u32 v70, v37, 4, v35
	v_or_b32_e32 v37, 24, v36
	v_bitop3_b32 v37, v34, v37, 14 bitop3:0x6c
	v_lshl_add_u32 v71, v37, 4, v35
	v_or_b32_e32 v37, 26, v36
	s_addc_u32 s27, s9, s5
	v_bitop3_b32 v37, v34, v37, 14 bitop3:0x6c
	s_mul_hi_i32 s2, s1, 0x28000
	s_mul_i32 s1, s1, 0x28000
	v_lshl_add_u32 v72, v37, 4, v35
	v_or_b32_e32 v37, 28, v36
	v_or_b32_e32 v36, 30, v36
	s_add_u32 s4, s64, s1
	v_bitop3_b32 v37, v34, v37, 14 bitop3:0x6c
	v_bitop3_b32 v34, v34, v36, 14 bitop3:0x6c
	s_addc_u32 s5, s65, s2
	v_lshl_add_u32 v73, v37, 4, v35
	v_lshl_add_u32 v74, v34, 4, v35
	v_lshl_add_u64 v[152:153], s[4:5], 0, v[0:1]
	v_mov_b32_e32 v36, v1
	v_mov_b32_e32 v37, v1
	v_lshlrev_b32_e32 v0, 2, v38
	v_add_u32_e32 v38, 0, v39
	v_mov_b32_e32 v34, v1
	v_mov_b32_e32 v35, v1
	v_add_u32_e32 v167, v59, v58
	v_add_u32_e32 v168, v60, v58
	v_add_u32_e32 v169, v61, v58
	v_add_u32_e32 v170, v62, v58
	v_add_u32_e32 v171, v63, v58
	v_add_u32_e32 v172, v64, v58
	v_add_u32_e32 v173, v65, v58
	v_add_u32_e32 v174, v66, v58
	v_add_u32_e32 v175, v67, v58
	v_add_u32_e32 v176, v68, v58
	v_add_u32_e32 v177, v69, v58
	v_add_u32_e32 v178, v70, v58
	v_add_u32_e32 v179, v71, v58
	v_add_u32_e32 v180, v72, v58
	v_add_u32_e32 v181, v73, v58
	v_add_u32_e32 v182, v74, v58
	v_add_u32_e32 v186, v44, v40
	v_add_u32_e32 v187, v45, v40
	v_add_u32_e32 v188, v47, v40
	v_add_u32_e32 v189, v48, v40
	v_add_u32_e32 v190, v49, v40
	v_add_u32_e32 v191, v46, v51
	v_add_u32_e32 v192, 0x21000, v38
	v_add_u32_e32 v193, v46, v50
	v_add_u32_e32 v194, v46, v52
	v_add_u32_e32 v195, v46, v53
	v_add_u32_e32 v196, v46, v54
	v_add_u32_e32 v197, v46, v55
	v_add_u32_e32 v198, v46, v56
	v_add_u32_e32 v199, v46, v57
	v_mov_b64_e32 v[96:97], v[36:37]
	v_mov_b64_e32 v[92:93], v[36:37]
	v_mov_b64_e32 v[88:89], v[36:37]
	v_mov_b64_e32 v[84:85], v[36:37]
	v_mov_b64_e32 v[80:81], v[36:37]
	v_mov_b64_e32 v[76:77], v[36:37]
	v_mov_b64_e32 v[72:73], v[36:37]
	v_mov_b64_e32 v[68:69], v[36:37]
	v_mov_b64_e32 v[64:65], v[36:37]
	v_mov_b64_e32 v[60:61], v[36:37]
	v_mov_b64_e32 v[56:57], v[36:37]
	v_mov_b64_e32 v[52:53], v[36:37]
	v_mov_b64_e32 v[48:49], v[36:37]
	v_mov_b64_e32 v[44:45], v[36:37]
	v_mov_b64_e32 v[40:41], v[36:37]
	v_mov_b64_e32 v[94:95], v[34:35]
	v_mov_b64_e32 v[90:91], v[34:35]
	v_mov_b64_e32 v[86:87], v[34:35]
	v_mov_b64_e32 v[82:83], v[34:35]
	v_mov_b64_e32 v[78:79], v[34:35]
	v_mov_b64_e32 v[74:75], v[34:35]
	v_mov_b64_e32 v[70:71], v[34:35]
	v_mov_b64_e32 v[66:67], v[34:35]
	v_mov_b64_e32 v[62:63], v[34:35]
	v_mov_b64_e32 v[58:59], v[34:35]
	v_mov_b64_e32 v[54:55], v[34:35]
	v_mov_b64_e32 v[50:51], v[34:35]
	v_mov_b64_e32 v[46:47], v[34:35]
	v_mov_b64_e32 v[42:43], v[34:35]
	v_mov_b64_e32 v[38:39], v[34:35]
	s_waitcnt vmcnt(0)
	s_branch .LBB0_2500

.LBB0_2509:
	s_and_b32 s2, s31, 0x60
	s_lshl_b32 s8, s2, 10
	s_add_u32 s8, s28, s8
	s_addc_u32 s9, s29, 0
	v_lshl_add_u64 v[98:99], s[8:9], 0, v[0:1]
	v_add_co_u32_e32 v102, vcc, 0x2000, v98
	v_lshl_add_u64 v[100:101], v[98:99], 0, s[78:79]
	s_nop 0
	v_addc_co_u32_e32 v103, vcc, 0, v99, vcc
	v_add_co_u32_e32 v98, vcc, 0x3000, v98
	global_load_dwordx4 v[138:141], v[100:101], off offset:1024
	global_load_dwordx4 v[134:137], v[100:101], off offset:2048
	global_load_dwordx4 v[142:145], v[102:103], off
	global_load_dwordx4 v[130:133], v[100:101], off offset:3072
	v_addc_co_u32_e32 v99, vcc, 0, v99, vcc
	global_load_dwordx4 v[126:129], v[98:99], off
	global_load_dwordx4 v[122:125], v[98:99], off offset:1024
	global_load_dwordx4 v[118:121], v[98:99], off offset:2048
	global_load_dwordx4 v[114:117], v[98:99], off offset:3072
	s_mov_b64 s[46:47], 0x4000
	v_lshl_add_u64 v[250:251], v[100:101], 0, s[46:47]
	v_lshl_add_u64 v[252:253], v[98:99], 0, s[46:47]
	global_load_dwordx4 v[202:205], v[250:251], off offset:1024
	global_load_dwordx4 v[206:209], v[250:251], off offset:2048
	global_load_dwordx4 v[210:213], v[250:251], off
	global_load_dwordx4 v[214:217], v[250:251], off offset:3072
	global_load_dwordx4 v[218:221], v[252:253], off
	global_load_dwordx4 v[222:225], v[252:253], off offset:1024
	global_load_dwordx4 v[226:229], v[252:253], off offset:2048
	global_load_dwordx4 v[230:233], v[252:253], off offset:3072
	v_cndmask_b32_e64 v98, 0, 1, s[4:5]
	v_cmp_ne_u32_e64 s[8:9], 1, v98
	s_andn2_b64 vcc, exec, s[4:5]
	s_mov_b64 s[28:29], s[14:15]
	s_cbranch_vccnz .LBB0_2518
	s_cmp_lt_i32 s1, 2
	s_cbranch_scc1 .LBB0_2514
	s_cmp_eq_u32 s1, 2
	s_mov_b64 s[4:5], -1
	s_cbranch_scc0 .LBB0_2513
	s_mov_b64 s[4:5], 0

.LBB0_2518:
	v_or_b32_e32 v98, s2, v155
	v_lshlrev_b32_e32 v98, 8, v98
	v_mov_b32_e32 v99, v1
	v_lshl_add_u64 v[98:99], s[28:29], 0, v[98:99]
	v_lshl_add_u64 v[98:99], v[150:151], 2, v[98:99]
	global_load_dwordx4 v[110:113], v[98:99], off offset:16
	global_load_dwordx4 v[106:109], v[98:99], off
	global_load_dwordx4 v[102:105], v[98:99], off offset:144
	s_nop 0
	global_load_dwordx4 v[98:101], v[98:99], off offset:128
	s_waitcnt vmcnt(37)
	v_cvt_pk_bf16_f32 v22, v22, v23
	v_cvt_pk_bf16_f32 v23, v24, v25
	ds_write_b64 v183, v[22:23]
	s_waitcnt vmcnt(36)
	v_cvt_pk_bf16_f32 v14, v14, v15
	v_cvt_pk_bf16_f32 v15, v16, v17
	ds_write_b64 v184, v[14:15] offset:512
	s_waitcnt vmcnt(35)
	v_cvt_pk_bf16_f32 v6, v6, v7
	v_cvt_pk_bf16_f32 v7, v8, v9
	ds_write_b64 v185, v[6:7] offset:1024
	s_waitcnt vmcnt(34)
	v_cvt_pk_bf16_f32 v2, v2, v3
	v_cvt_pk_bf16_f32 v3, v4, v5
	ds_write_b64 v186, v[2:3] offset:1536
	s_waitcnt vmcnt(33)
	v_cvt_pk_bf16_f32 v2, v30, v31
	v_cvt_pk_bf16_f32 v3, v32, v33
	ds_write_b64 v187, v[2:3] offset:2048
	s_waitcnt vmcnt(32)
	v_cvt_pk_bf16_f32 v2, v26, v27
	v_cvt_pk_bf16_f32 v3, v28, v29
	ds_write_b64 v188, v[2:3] offset:2560
	s_waitcnt vmcnt(31)
	v_cvt_pk_bf16_f32 v2, v18, v19
	v_cvt_pk_bf16_f32 v3, v20, v21
	ds_write_b64 v189, v[2:3] offset:3072
	s_waitcnt vmcnt(30)
	v_cvt_pk_bf16_f32 v2, v10, v11
	v_cvt_pk_bf16_f32 v3, v12, v13
	ds_write_b64 v190, v[2:3] offset:3584
	s_and_b64 vcc, exec, s[8:9]
	s_mov_b64 s[4:5], s[12:13]
	s_cbranch_vccnz .LBB0_2527
	s_cmp_lt_i32 s1, 2
	s_cbranch_scc1 .LBB0_2523
	s_cmp_eq_u32 s1, 2
	s_mov_b64 s[28:29], -1
	s_cbranch_scc0 .LBB0_2522
	s_mov_b64 s[28:29], 0

.LBB0_2527:
	s_add_i32 s28, s34, 0xffffe000
	s_and_b32 s28, s28, 0x6000
	s_lshl_b32 s28, s28, 2
	s_add_u32 s4, s4, s28
	s_addc_u32 s5, s5, 0
	v_lshl_add_u64 v[2:3], s[4:5], 0, v[0:1]
	s_mov_b64 s[4:5], 0x4000
	v_lshl_add_u64 v[4:5], v[2:3], 0, s[4:5]
	s_movk_i32 s4, 0x5000
	v_add_co_u32_e32 v10, vcc, s4, v2
	s_nop 1
	v_addc_co_u32_e32 v11, vcc, 0, v3, vcc
	global_load_dwordx4 v[14:17], v[4:5], off offset:1024
	global_load_dwordx4 v[6:9], v[4:5], off offset:2048
	global_load_dwordx4 v[22:25], v[10:11], off offset:-4096
	s_nop 0
	global_load_dwordx4 v[2:5], v[4:5], off offset:3072
	s_nop 0
	global_load_dwordx4 v[30:33], v[10:11], off
	global_load_dwordx4 v[26:29], v[10:11], off offset:1024
	global_load_dwordx4 v[18:21], v[10:11], off offset:2048
	s_nop 0
	global_load_dwordx4 v[10:13], v[10:11], off offset:3072
	s_waitcnt vmcnt(25)
	v_cvt_pk_bf16_f32 v142, v142, v143
	v_cvt_pk_bf16_f32 v143, v144, v145
	ds_write_b64 v183, v[142:143] offset:4096
	v_cvt_pk_bf16_f32 v138, v138, v139
	v_cvt_pk_bf16_f32 v139, v140, v141
	ds_write_b64 v184, v[138:139] offset:4608
	v_cvt_pk_bf16_f32 v134, v134, v135
	v_cvt_pk_bf16_f32 v135, v136, v137
	ds_write_b64 v185, v[134:135] offset:5120
	s_waitcnt vmcnt(24)
	v_cvt_pk_bf16_f32 v130, v130, v131
	v_cvt_pk_bf16_f32 v131, v132, v133
	ds_write_b64 v186, v[130:131] offset:5632
	s_waitcnt vmcnt(23)
	v_cvt_pk_bf16_f32 v126, v126, v127
	v_cvt_pk_bf16_f32 v127, v128, v129
	ds_write_b64 v187, v[126:127] offset:6144
	s_waitcnt vmcnt(22)
	v_cvt_pk_bf16_f32 v122, v122, v123
	v_cvt_pk_bf16_f32 v123, v124, v125
	ds_write_b64 v188, v[122:123] offset:6656
	s_waitcnt vmcnt(21)
	v_cvt_pk_bf16_f32 v118, v118, v119
	v_cvt_pk_bf16_f32 v119, v120, v121
	ds_write_b64 v189, v[118:119] offset:7168
	s_waitcnt vmcnt(20)
	v_cvt_pk_bf16_f32 v114, v114, v115
	v_cvt_pk_bf16_f32 v115, v116, v117
	ds_write_b64 v190, v[114:115] offset:7680
	ds_read_b128 v[114:117], v191
	v_mov_b32_e32 v119, v1
	s_waitcnt lgkmcnt(0)
	v_lshlrev_b32_e32 v121, 16, v116
	v_and_b32_e32 v122, 0xffff0000, v116
	v_cvt_pk_fp8_f32 v119, v121, v122
	v_lshlrev_b32_e32 v118, 16, v117
	v_and_b32_e32 v120, 0xffff0000, v117
	v_lshlrev_b32_e32 v122, 16, v114
	v_cvt_pk_fp8_f32 v119, v118, v120 op_sel:[0,0,1]
	v_and_b32_e32 v123, 0xffff0000, v114
	v_mov_b32_e32 v118, v1
	v_cvt_pk_fp8_f32 v118, v122, v123
	v_lshlrev_b32_e32 v120, 16, v115
	v_and_b32_e32 v121, 0xffff0000, v115
	v_mov_b32_e32 v123, v1
	v_cvt_pk_fp8_f32 v118, v120, v121 op_sel:[0,0,1]
	global_store_dwordx2 v[152:153], v[118:119], off
	ds_read_b128 v[118:121], v192
	s_waitcnt lgkmcnt(0)
	v_mfma_f32_16x16x32_bf16 v[114:117], v[114:117], v[118:121], 0
	ds_read_b128 v[118:121], v193
	s_waitcnt lgkmcnt(0)
	v_lshlrev_b32_e32 v125, 16, v120
	v_and_b32_e32 v126, 0xffff0000, v120
	v_cvt_pk_fp8_f32 v123, v125, v126
	v_lshlrev_b32_e32 v122, 16, v121
	v_and_b32_e32 v124, 0xffff0000, v121
	v_lshlrev_b32_e32 v126, 16, v118
	v_cvt_pk_fp8_f32 v123, v122, v124 op_sel:[0,0,1]
	v_and_b32_e32 v127, 0xffff0000, v118
	v_mov_b32_e32 v122, v1
	v_cvt_pk_fp8_f32 v122, v126, v127
	v_lshlrev_b32_e32 v124, 16, v119
	v_and_b32_e32 v125, 0xffff0000, v119
	v_cvt_pk_fp8_f32 v122, v124, v125 op_sel:[0,0,1]
	global_store_dwordx2 v[152:153], v[122:123], off offset:512
	ds_read_b128 v[122:125], v192 offset:1024
	s_waitcnt lgkmcnt(0)
	v_mfma_f32_16x16x32_bf16 v[114:117], v[118:121], v[122:125], v[114:117]
	ds_read_b128 v[118:121], v194
	v_mov_b32_e32 v123, v1
	s_waitcnt lgkmcnt(0)
	v_lshlrev_b32_e32 v125, 16, v120
	v_and_b32_e32 v126, 0xffff0000, v120
	v_cvt_pk_fp8_f32 v123, v125, v126
	v_lshlrev_b32_e32 v122, 16, v121
	v_and_b32_e32 v124, 0xffff0000, v121
	v_lshlrev_b32_e32 v126, 16, v118
	v_cvt_pk_fp8_f32 v123, v122, v124 op_sel:[0,0,1]
	v_and_b32_e32 v127, 0xffff0000, v118
	v_mov_b32_e32 v122, v1
	v_cvt_pk_fp8_f32 v122, v126, v127
	v_lshlrev_b32_e32 v124, 16, v119
	v_and_b32_e32 v125, 0xffff0000, v119
	v_cvt_pk_fp8_f32 v122, v124, v125 op_sel:[0,0,1]
	global_store_dwordx2 v[152:153], v[122:123], off offset:1024
	ds_read_b128 v[122:125], v192 offset:2048
	s_waitcnt lgkmcnt(0)
	v_mfma_f32_16x16x32_bf16 v[114:117], v[118:121], v[122:125], v[114:117]
	ds_read_b128 v[118:121], v195
	v_mov_b32_e32 v123, v1
	s_waitcnt lgkmcnt(0)
	v_lshlrev_b32_e32 v125, 16, v120
	v_and_b32_e32 v126, 0xffff0000, v120
	v_cvt_pk_fp8_f32 v123, v125, v126
	v_lshlrev_b32_e32 v122, 16, v121
	v_and_b32_e32 v124, 0xffff0000, v121
	v_lshlrev_b32_e32 v126, 16, v118
	v_cvt_pk_fp8_f32 v123, v122, v124 op_sel:[0,0,1]
	v_and_b32_e32 v127, 0xffff0000, v118
	v_mov_b32_e32 v122, v1
	v_cvt_pk_fp8_f32 v122, v126, v127
	v_lshlrev_b32_e32 v124, 16, v119
	v_and_b32_e32 v125, 0xffff0000, v119
	v_cvt_pk_fp8_f32 v122, v124, v125 op_sel:[0,0,1]
	global_store_dwordx2 v[152:153], v[122:123], off offset:1536
	ds_read_b128 v[122:125], v192 offset:3072
	s_waitcnt lgkmcnt(0)
	v_mfma_f32_16x16x32_bf16 v[114:117], v[118:121], v[122:125], v[114:117]
	ds_read_b128 v[118:121], v196
	v_mov_b32_e32 v123, v1
	s_waitcnt lgkmcnt(0)
	v_lshlrev_b32_e32 v125, 16, v120
	v_and_b32_e32 v126, 0xffff0000, v120
	v_cvt_pk_fp8_f32 v123, v125, v126
	v_lshlrev_b32_e32 v122, 16, v121
	v_and_b32_e32 v124, 0xffff0000, v121
	v_lshlrev_b32_e32 v126, 16, v118
	v_cvt_pk_fp8_f32 v123, v122, v124 op_sel:[0,0,1]
	v_and_b32_e32 v127, 0xffff0000, v118
	v_mov_b32_e32 v122, v1
	v_cvt_pk_fp8_f32 v122, v126, v127
	v_lshlrev_b32_e32 v124, 16, v119
	v_and_b32_e32 v125, 0xffff0000, v119
	v_cvt_pk_fp8_f32 v122, v124, v125 op_sel:[0,0,1]
	global_store_dwordx2 v[152:153], v[122:123], off offset:2048
	ds_read_b128 v[122:125], v192 offset:4096
	s_waitcnt lgkmcnt(0)
	v_mfma_f32_16x16x32_bf16 v[114:117], v[118:121], v[122:125], v[114:117]
	ds_read_b128 v[118:121], v197
	v_mov_b32_e32 v123, v1
	s_waitcnt lgkmcnt(0)
	v_lshlrev_b32_e32 v125, 16, v120
	v_and_b32_e32 v126, 0xffff0000, v120
	v_cvt_pk_fp8_f32 v123, v125, v126
	v_lshlrev_b32_e32 v122, 16, v121
	v_and_b32_e32 v124, 0xffff0000, v121
	v_lshlrev_b32_e32 v126, 16, v118
	v_cvt_pk_fp8_f32 v123, v122, v124 op_sel:[0,0,1]
	v_and_b32_e32 v127, 0xffff0000, v118
	v_mov_b32_e32 v122, v1
	v_cvt_pk_fp8_f32 v122, v126, v127
	v_lshlrev_b32_e32 v124, 16, v119
	v_and_b32_e32 v125, 0xffff0000, v119
	v_cvt_pk_fp8_f32 v122, v124, v125 op_sel:[0,0,1]
	global_store_dwordx2 v[152:153], v[122:123], off offset:2560
	ds_read_b128 v[122:125], v192 offset:5120
	s_waitcnt lgkmcnt(0)
	v_mfma_f32_16x16x32_bf16 v[114:117], v[118:121], v[122:125], v[114:117]
	ds_read_b128 v[118:121], v198
	v_mov_b32_e32 v123, v1
	s_waitcnt lgkmcnt(0)
	v_lshlrev_b32_e32 v125, 16, v120
	v_and_b32_e32 v126, 0xffff0000, v120
	v_cvt_pk_fp8_f32 v123, v125, v126
	v_lshlrev_b32_e32 v122, 16, v121
	v_and_b32_e32 v124, 0xffff0000, v121
	v_lshlrev_b32_e32 v126, 16, v118
	v_cvt_pk_fp8_f32 v123, v122, v124 op_sel:[0,0,1]
	v_and_b32_e32 v127, 0xffff0000, v118
	v_mov_b32_e32 v122, v1
	v_cvt_pk_fp8_f32 v122, v126, v127
	v_lshlrev_b32_e32 v124, 16, v119
	v_and_b32_e32 v125, 0xffff0000, v119
	v_cvt_pk_fp8_f32 v122, v124, v125 op_sel:[0,0,1]
	global_store_dwordx2 v[152:153], v[122:123], off offset:3072
	ds_read_b128 v[122:125], v192 offset:6144
	s_waitcnt lgkmcnt(0)
	v_mfma_f32_16x16x32_bf16 v[114:117], v[118:121], v[122:125], v[114:117]
	ds_read_b128 v[118:121], v199
	v_mov_b32_e32 v123, v1
	s_waitcnt lgkmcnt(0)
	v_lshlrev_b32_e32 v125, 16, v120
	v_and_b32_e32 v126, 0xffff0000, v120
	v_cvt_pk_fp8_f32 v123, v125, v126
	v_lshlrev_b32_e32 v122, 16, v121
	v_and_b32_e32 v124, 0xffff0000, v121
	v_lshlrev_b32_e32 v126, 16, v118
	v_cvt_pk_fp8_f32 v123, v122, v124 op_sel:[0,0,1]
	v_and_b32_e32 v127, 0xffff0000, v118
	v_mov_b32_e32 v122, v1
	v_cvt_pk_fp8_f32 v122, v126, v127
	v_lshlrev_b32_e32 v124, 16, v119
	v_and_b32_e32 v125, 0xffff0000, v119
	v_cvt_pk_fp8_f32 v122, v124, v125 op_sel:[0,0,1]
	global_store_dwordx2 v[152:153], v[122:123], off offset:3584
	ds_read_b128 v[122:125], v192 offset:7168
	s_waitcnt lgkmcnt(0)
	v_mfma_f32_16x16x32_bf16 v[114:117], v[118:121], v[122:125], v[114:117]
	v_mov_b32_e32 v122, v1
	s_waitcnt vmcnt(18)
	v_cvt_pk_fp8_f32 v122, v106, v107
	v_cvt_pk_bf16_f32 v118, v106, v107
	v_cvt_pk_bf16_f32 v119, v108, v109
	v_cvt_pk_bf16_f32 v120, v110, v111
	v_cvt_pk_bf16_f32 v121, v112, v113
	v_cvt_pk_fp8_f32 v122, v108, v109 op_sel:[0,0,1]
	ds_read_b128 v[106:109], v192 offset:8192
	v_mov_b32_e32 v123, v1
	v_cvt_pk_fp8_f32 v123, v110, v111
	s_waitcnt lgkmcnt(0)
	v_mfma_f32_16x16x32_bf16 v[106:109], v[118:121], v[106:109], v[114:117]
	v_cvt_pk_fp8_f32 v123, v112, v113 op_sel:[0,0,1]
	s_nop 1
	v_mov_b32_e32 v114, v1
	s_waitcnt vmcnt(16)
	v_cvt_pk_fp8_f32 v114, v98, v99
	v_add_co_u32_e32 v156, vcc, s63, v152
	v_mov_b32_e32 v115, v1
	s_nop 0
	v_addc_co_u32_e32 v157, vcc, 0, v153, vcc
	global_store_dwordx2 v[156:157], v[122:123], off
	v_cvt_pk_bf16_f32 v110, v98, v99
	v_cvt_pk_bf16_f32 v111, v100, v101
	v_cvt_pk_bf16_f32 v112, v102, v103
	v_cvt_pk_bf16_f32 v113, v104, v105
	v_cvt_pk_fp8_f32 v114, v100, v101 op_sel:[0,0,1]
	ds_read_b128 v[98:101], v192 offset:9216
	v_cvt_pk_fp8_f32 v115, v102, v103
	s_waitcnt lgkmcnt(0)
	v_mfma_f32_16x16x32_bf16 v[98:101], v[110:113], v[98:101], v[106:109]
	v_cvt_pk_fp8_f32 v115, v104, v105 op_sel:[0,0,1]
	global_store_dwordx2 v[156:157], v[114:115], off offset:512
	s_and_b64 vcc, exec, s[8:9]
	s_mov_b64 s[28:29], s[12:13]
	s_cbranch_vccnz .LBB0_2536
	s_cmp_lt_i32 s1, 2
	s_cbranch_scc1 .LBB0_2532
	s_cmp_eq_u32 s1, 2
	s_mov_b64 s[4:5], -1
	s_cbranch_scc0 .LBB0_2531
	s_mov_b64 s[4:5], 0

.LBB0_2536:
	s_or_b32 s2, s2, 16
	s_lshl_b32 s4, s2, 10
	s_add_u32 s4, s28, s4
	s_addc_u32 s5, s29, 0
	v_lshl_add_u64 v[102:103], s[4:5], 0, v[0:1]
	v_add_co_u32_e32 v106, vcc, 0x2000, v102
	v_lshl_add_u64 v[104:105], v[102:103], 0, s[78:79]
	s_nop 0
	v_addc_co_u32_e32 v107, vcc, 0, v103, vcc
	v_add_co_u32_e32 v102, vcc, 0x3000, v102
	v_addc_co_u32_e32 v103, vcc, 0, v103, vcc
	s_and_b64 vcc, exec, s[8:9]
	s_mov_b64 s[8:9], s[14:15]
	s_cbranch_vccnz .LBB0_2545
	s_cmp_lt_i32 s1, 2
	s_cbranch_scc1 .LBB0_2541
	s_cmp_eq_u32 s1, 2
	s_mov_b64 s[4:5], -1
	s_cbranch_scc0 .LBB0_2540
	s_mov_b64 s[4:5], 0

.LBB0_2545:
	v_or_b32_e32 v102, s2, v155
	v_lshlrev_b32_e32 v102, 8, v102
	v_mov_b32_e32 v103, v1
	v_lshl_add_u64 v[102:103], s[8:9], 0, v[102:103]
	v_lshl_add_u64 v[102:103], v[150:151], 2, v[102:103]
	global_load_dwordx4 v[114:117], v[102:103], off offset:16
	global_load_dwordx4 v[110:113], v[102:103], off
	global_load_dwordx4 v[106:109], v[102:103], off offset:144
	s_nop 0
	global_load_dwordx4 v[102:105], v[102:103], off offset:128
	s_waitcnt vmcnt(19)
	v_cvt_pk_bf16_f32 v200, v22, v23
	v_cvt_pk_bf16_f32 v201, v24, v25
	ds_write_b64 v183, v[200:201] offset:8192
	v_cvt_pk_bf16_f32 v200, v14, v15
	v_cvt_pk_bf16_f32 v201, v16, v17
	ds_write_b64 v184, v[200:201] offset:8704
	v_cvt_pk_bf16_f32 v200, v6, v7
	v_cvt_pk_bf16_f32 v201, v8, v9
	ds_write_b64 v185, v[200:201] offset:9216
	s_waitcnt vmcnt(18)
	v_cvt_pk_bf16_f32 v200, v2, v3
	v_cvt_pk_bf16_f32 v201, v4, v5
	ds_write_b64 v186, v[200:201] offset:9728
	s_waitcnt vmcnt(17)
	v_cvt_pk_bf16_f32 v200, v30, v31
	v_cvt_pk_bf16_f32 v201, v32, v33
	ds_write_b64 v187, v[200:201] offset:10240
	s_waitcnt vmcnt(16)
	v_cvt_pk_bf16_f32 v200, v26, v27
	v_cvt_pk_bf16_f32 v201, v28, v29
	ds_write_b64 v188, v[200:201] offset:10752
	s_waitcnt vmcnt(15)
	v_cvt_pk_bf16_f32 v200, v18, v19
	v_cvt_pk_bf16_f32 v201, v20, v21
	ds_write_b64 v189, v[200:201] offset:11264
	s_waitcnt vmcnt(14)
	v_cvt_pk_bf16_f32 v200, v10, v11
	v_cvt_pk_bf16_f32 v201, v12, v13
	ds_write_b64 v190, v[200:201] offset:11776
	s_cmp_gt_u32 s35, 59
	s_cbranch_scc1 .Lmy_a2B_stub
	s_cmp_lt_u32 s35, 12
	s_mov_b64 s[4:5], s[12:13]
	s_cbranch_scc1 .LBB0_2552
	s_lshr_b32 s1, s30, 4
	s_cmp_lt_i32 s1, 2
	s_mov_b64 s[4:5], s[16:17]
	s_cbranch_scc1 .LBB0_2552
	s_cmp_lg_u32 s1, 2
	s_mov_b64 s[4:5], -1
	s_cbranch_scc0 .LBB0_2550
	s_mov_b64 s[4:5], 0

.LBB0_2553:
	v_cvt_pk_bf16_f32 v210, v210, v211
	v_cvt_pk_bf16_f32 v211, v212, v213
	ds_write_b64 v183, v[210:211] offset:12288
	v_cvt_pk_bf16_f32 v202, v202, v203
	v_cvt_pk_bf16_f32 v203, v204, v205
	ds_write_b64 v184, v[202:203] offset:12800
	v_cvt_pk_bf16_f32 v206, v206, v207
	v_cvt_pk_bf16_f32 v207, v208, v209
	ds_write_b64 v185, v[206:207] offset:13312
	v_cvt_pk_bf16_f32 v214, v214, v215
	v_cvt_pk_bf16_f32 v215, v216, v217
	ds_write_b64 v186, v[214:215] offset:13824
	v_cvt_pk_bf16_f32 v218, v218, v219
	v_cvt_pk_bf16_f32 v219, v220, v221
	ds_write_b64 v187, v[218:219] offset:14336
	v_cvt_pk_bf16_f32 v222, v222, v223
	v_cvt_pk_bf16_f32 v223, v224, v225
	ds_write_b64 v188, v[222:223] offset:14848
	v_cvt_pk_bf16_f32 v226, v226, v227
	v_cvt_pk_bf16_f32 v227, v228, v229
	ds_write_b64 v189, v[226:227] offset:15360
	v_cvt_pk_bf16_f32 v230, v230, v231
	v_cvt_pk_bf16_f32 v231, v232, v233
	ds_write_b64 v190, v[230:231] offset:15872
	ds_read_b128 v[118:121], v191 offset:8192
	v_mov_b32_e32 v123, v1
	s_waitcnt lgkmcnt(0)
	v_lshlrev_b32_e32 v125, 16, v120
	v_and_b32_e32 v126, 0xffff0000, v120
	v_cvt_pk_fp8_f32 v123, v125, v126
	v_lshlrev_b32_e32 v122, 16, v121
	v_and_b32_e32 v124, 0xffff0000, v121
	v_lshlrev_b32_e32 v126, 16, v118
	v_cvt_pk_fp8_f32 v123, v122, v124 op_sel:[0,0,1]
	v_and_b32_e32 v127, 0xffff0000, v118
	v_mov_b32_e32 v122, v1
	v_cvt_pk_fp8_f32 v122, v126, v127
	v_lshlrev_b32_e32 v124, 16, v119
	v_and_b32_e32 v125, 0xffff0000, v119
	v_mov_b32_e32 v127, v1
	v_cvt_pk_fp8_f32 v122, v124, v125 op_sel:[0,0,1]
	global_store_dwordx2 v[156:157], v[122:123], off offset:1024
	ds_read_b128 v[122:125], v192
	s_waitcnt lgkmcnt(0)
	v_mfma_f32_16x16x32_bf16 v[118:121], v[118:121], v[122:125], 0
	ds_read_b128 v[122:125], v193 offset:8192
	s_waitcnt lgkmcnt(0)
	v_lshlrev_b32_e32 v129, 16, v124
	v_and_b32_e32 v130, 0xffff0000, v124
	v_cvt_pk_fp8_f32 v127, v129, v130
	v_lshlrev_b32_e32 v126, 16, v125
	v_and_b32_e32 v128, 0xffff0000, v125
	v_lshlrev_b32_e32 v130, 16, v122
	v_cvt_pk_fp8_f32 v127, v126, v128 op_sel:[0,0,1]
	v_and_b32_e32 v131, 0xffff0000, v122
	v_mov_b32_e32 v126, v1
	v_cvt_pk_fp8_f32 v126, v130, v131
	v_lshlrev_b32_e32 v128, 16, v123
	v_and_b32_e32 v129, 0xffff0000, v123
	v_cvt_pk_fp8_f32 v126, v128, v129 op_sel:[0,0,1]
	global_store_dwordx2 v[156:157], v[126:127], off offset:1536
	ds_read_b128 v[126:129], v192 offset:1024
	s_waitcnt lgkmcnt(0)
	v_mfma_f32_16x16x32_bf16 v[118:121], v[122:125], v[126:129], v[118:121]
	ds_read_b128 v[122:125], v194 offset:8192
	v_mov_b32_e32 v127, v1
	s_waitcnt lgkmcnt(0)
	v_lshlrev_b32_e32 v129, 16, v124
	v_and_b32_e32 v130, 0xffff0000, v124
	v_cvt_pk_fp8_f32 v127, v129, v130
	v_lshlrev_b32_e32 v126, 16, v125
	v_and_b32_e32 v128, 0xffff0000, v125
	v_lshlrev_b32_e32 v130, 16, v122
	v_cvt_pk_fp8_f32 v127, v126, v128 op_sel:[0,0,1]
	v_and_b32_e32 v131, 0xffff0000, v122
	v_mov_b32_e32 v126, v1
	v_cvt_pk_fp8_f32 v126, v130, v131
	v_lshlrev_b32_e32 v128, 16, v123
	v_and_b32_e32 v129, 0xffff0000, v123
	v_cvt_pk_fp8_f32 v126, v128, v129 op_sel:[0,0,1]
	global_store_dwordx2 v[156:157], v[126:127], off offset:2048
	ds_read_b128 v[126:129], v192 offset:2048
	s_waitcnt lgkmcnt(0)
	v_mfma_f32_16x16x32_bf16 v[118:121], v[122:125], v[126:129], v[118:121]
	ds_read_b128 v[122:125], v195 offset:8192
	v_mov_b32_e32 v127, v1
	s_waitcnt lgkmcnt(0)
	v_lshlrev_b32_e32 v129, 16, v124
	v_and_b32_e32 v130, 0xffff0000, v124
	v_cvt_pk_fp8_f32 v127, v129, v130
	v_lshlrev_b32_e32 v126, 16, v125
	v_and_b32_e32 v128, 0xffff0000, v125
	v_lshlrev_b32_e32 v130, 16, v122
	v_cvt_pk_fp8_f32 v127, v126, v128 op_sel:[0,0,1]
	v_and_b32_e32 v131, 0xffff0000, v122
	v_mov_b32_e32 v126, v1
	v_cvt_pk_fp8_f32 v126, v130, v131
	v_lshlrev_b32_e32 v128, 16, v123
	v_and_b32_e32 v129, 0xffff0000, v123
	v_cvt_pk_fp8_f32 v126, v128, v129 op_sel:[0,0,1]
	global_store_dwordx2 v[156:157], v[126:127], off offset:2560
	ds_read_b128 v[126:129], v192 offset:3072
	s_waitcnt lgkmcnt(0)
	v_mfma_f32_16x16x32_bf16 v[118:121], v[122:125], v[126:129], v[118:121]
	ds_read_b128 v[122:125], v196 offset:8192
	v_mov_b32_e32 v127, v1
	s_waitcnt lgkmcnt(0)
	v_lshlrev_b32_e32 v129, 16, v124
	v_and_b32_e32 v130, 0xffff0000, v124
	v_cvt_pk_fp8_f32 v127, v129, v130
	v_lshlrev_b32_e32 v126, 16, v125
	v_and_b32_e32 v128, 0xffff0000, v125
	v_lshlrev_b32_e32 v130, 16, v122
	v_cvt_pk_fp8_f32 v127, v126, v128 op_sel:[0,0,1]
	v_and_b32_e32 v131, 0xffff0000, v122
	v_mov_b32_e32 v126, v1
	v_cvt_pk_fp8_f32 v126, v130, v131
	v_lshlrev_b32_e32 v128, 16, v123
	v_and_b32_e32 v129, 0xffff0000, v123
	v_cvt_pk_fp8_f32 v126, v128, v129 op_sel:[0,0,1]
	global_store_dwordx2 v[156:157], v[126:127], off offset:3072
	ds_read_b128 v[126:129], v192 offset:4096
	s_waitcnt lgkmcnt(0)
	v_mfma_f32_16x16x32_bf16 v[118:121], v[122:125], v[126:129], v[118:121]
	ds_read_b128 v[122:125], v197 offset:8192
	v_mov_b32_e32 v127, v1
	s_waitcnt lgkmcnt(0)
	v_lshlrev_b32_e32 v129, 16, v124
	v_and_b32_e32 v130, 0xffff0000, v124
	v_cvt_pk_fp8_f32 v127, v129, v130
	v_lshlrev_b32_e32 v126, 16, v125
	v_and_b32_e32 v128, 0xffff0000, v125
	v_lshlrev_b32_e32 v130, 16, v122
	v_cvt_pk_fp8_f32 v127, v126, v128 op_sel:[0,0,1]
	v_and_b32_e32 v131, 0xffff0000, v122
	v_mov_b32_e32 v126, v1
	v_cvt_pk_fp8_f32 v126, v130, v131
	v_lshlrev_b32_e32 v128, 16, v123
	v_and_b32_e32 v129, 0xffff0000, v123
	v_cvt_pk_fp8_f32 v126, v128, v129 op_sel:[0,0,1]
	global_store_dwordx2 v[156:157], v[126:127], off offset:3584
	ds_read_b128 v[126:129], v192 offset:5120
	s_waitcnt lgkmcnt(0)
	v_mfma_f32_16x16x32_bf16 v[120:123], v[122:125], v[126:129], v[118:121]
	ds_read_b128 v[124:127], v198 offset:8192
	v_mov_b32_e32 v129, v1
	s_movk_i32 s1, 0x2000
	s_waitcnt lgkmcnt(0)
	v_lshlrev_b32_e32 v128, 16, v126
	v_and_b32_e32 v130, 0xffff0000, v126
	v_cvt_pk_fp8_f32 v129, v128, v130
	v_lshlrev_b32_e32 v130, 16, v124
	v_and_b32_e32 v131, 0xffff0000, v124
	v_mov_b32_e32 v128, v1
	v_cvt_pk_fp8_f32 v128, v130, v131
	v_lshlrev_b32_e32 v118, 16, v127
	v_and_b32_e32 v119, 0xffff0000, v127
	v_cvt_pk_fp8_f32 v129, v118, v119 op_sel:[0,0,1]
	v_lshlrev_b32_e32 v118, 16, v125
	v_and_b32_e32 v119, 0xffff0000, v125
	v_cvt_pk_fp8_f32 v128, v118, v119 op_sel:[0,0,1]
	v_add_co_u32_e32 v118, vcc, s1, v152
	s_nop 1
	v_addc_co_u32_e32 v119, vcc, 0, v153, vcc
	global_store_dwordx2 v[118:119], v[128:129], off
	ds_read_b128 v[128:131], v192 offset:6144
	s_waitcnt lgkmcnt(0)
	v_mfma_f32_16x16x32_bf16 v[120:123], v[124:127], v[128:131], v[120:123]
	ds_read_b128 v[124:127], v199 offset:8192
	v_mov_b32_e32 v129, v1
	s_waitcnt lgkmcnt(0)
	v_lshlrev_b32_e32 v131, 16, v126
	v_and_b32_e32 v132, 0xffff0000, v126
	v_cvt_pk_fp8_f32 v129, v131, v132
	v_lshlrev_b32_e32 v128, 16, v127
	v_and_b32_e32 v130, 0xffff0000, v127
	v_lshlrev_b32_e32 v132, 16, v124
	v_cvt_pk_fp8_f32 v129, v128, v130 op_sel:[0,0,1]
	v_and_b32_e32 v133, 0xffff0000, v124
	v_mov_b32_e32 v128, v1
	v_cvt_pk_fp8_f32 v128, v132, v133
	v_lshlrev_b32_e32 v130, 16, v125
	v_and_b32_e32 v131, 0xffff0000, v125
	v_cvt_pk_fp8_f32 v128, v130, v131 op_sel:[0,0,1]
	global_store_dwordx2 v[118:119], v[128:129], off offset:512
	ds_read_b128 v[128:131], v192 offset:7168
	s_waitcnt lgkmcnt(0)
	v_mfma_f32_16x16x32_bf16 v[120:123], v[124:127], v[128:131], v[120:123]
	v_mov_b32_e32 v128, v1
	s_waitcnt vmcnt(18)
	v_cvt_pk_fp8_f32 v128, v110, v111
	v_cvt_pk_bf16_f32 v124, v110, v111
	v_cvt_pk_bf16_f32 v125, v112, v113
	v_cvt_pk_bf16_f32 v126, v114, v115
	v_cvt_pk_bf16_f32 v127, v116, v117
	v_cvt_pk_fp8_f32 v128, v112, v113 op_sel:[0,0,1]
	ds_read_b128 v[110:113], v192 offset:8192
	v_mov_b32_e32 v129, v1
	v_cvt_pk_fp8_f32 v129, v114, v115
	s_waitcnt lgkmcnt(0)
	v_mfma_f32_16x16x32_bf16 v[110:113], v[124:127], v[110:113], v[120:123]
	v_cvt_pk_fp8_f32 v129, v116, v117 op_sel:[0,0,1]
	s_nop 1
	v_mov_b32_e32 v120, v1
	s_waitcnt vmcnt(16)
	v_cvt_pk_fp8_f32 v120, v102, v103
	v_mov_b32_e32 v121, v1
	global_store_dwordx2 v[118:119], v[128:129], off offset:1024
	v_cvt_pk_bf16_f32 v114, v102, v103
	v_cvt_pk_bf16_f32 v115, v104, v105
	v_cvt_pk_bf16_f32 v116, v106, v107
	v_cvt_pk_bf16_f32 v117, v108, v109
	v_cvt_pk_fp8_f32 v120, v104, v105 op_sel:[0,0,1]
	ds_read_b128 v[102:105], v192 offset:9216
	v_cvt_pk_fp8_f32 v121, v106, v107
	s_waitcnt lgkmcnt(0)
	v_mfma_f32_16x16x32_bf16 v[102:105], v[114:117], v[102:105], v[110:113]
	v_cvt_pk_fp8_f32 v121, v108, v109 op_sel:[0,0,1]
	global_store_dwordx2 v[118:119], v[120:121], off offset:1536
	v_max_f32_e32 v106, v99, v99
	v_max_f32_e32 v107, v98, v98
	v_max_f32_e32 v106, v107, v106
	v_max_f32_e32 v107, v101, v101
	v_max_f32_e32 v108, v100, v100
	v_max_f32_e32 v107, v108, v107
	v_max_f32_e32 v108, v105, v105
	v_max_f32_e32 v109, v104, v104
	v_max_f32_e32 v108, v109, v108
	v_max3_f32 v108, v102, v103, v108
	v_max3_f32 v106, v106, v107, v108
	ds_bpermute_b32 v107, v165, v106
	s_waitcnt lgkmcnt(0)
	v_max_f32_e32 v107, v107, v107
	v_max_f32_e32 v106, v106, v107
	ds_bpermute_b32 v107, v164, v106
	s_waitcnt lgkmcnt(0)
	v_max_f32_e32 v107, v107, v107
	v_max_f32_e32 v106, v106, v107
	v_add_f32_e32 v107, 0x41000000, v154
	v_cmp_gt_f32_e32 vcc, v106, v107
	s_cbranch_vccz .LBB0_2499
	v_max_f32_e32 v106, v106, v106
	v_max_f32_e32 v107, v154, v154
	v_max_f32_e32 v107, v107, v106
	v_sub_f32_e32 v106, v154, v107
	v_exp_f32_e32 v106, v106
	v_mov_b32_e32 v154, v107
	v_pk_mul_f32 v[36:37], v[36:37], v[106:107] op_sel_hi:[1,0]
	v_pk_mul_f32 v[34:35], v[34:35], v[106:107] op_sel_hi:[1,0]
	v_pk_mul_f32 v[96:97], v[96:97], v[106:107] op_sel_hi:[1,0]
	v_pk_mul_f32 v[94:95], v[94:95], v[106:107] op_sel_hi:[1,0]
	v_pk_mul_f32 v[92:93], v[92:93], v[106:107] op_sel_hi:[1,0]
	v_pk_mul_f32 v[90:91], v[90:91], v[106:107] op_sel_hi:[1,0]
	v_pk_mul_f32 v[88:89], v[88:89], v[106:107] op_sel_hi:[1,0]
	v_pk_mul_f32 v[86:87], v[86:87], v[106:107] op_sel_hi:[1,0]
	v_pk_mul_f32 v[84:85], v[84:85], v[106:107] op_sel_hi:[1,0]
	v_pk_mul_f32 v[82:83], v[82:83], v[106:107] op_sel_hi:[1,0]
	v_pk_mul_f32 v[80:81], v[80:81], v[106:107] op_sel_hi:[1,0]
	v_pk_mul_f32 v[78:79], v[78:79], v[106:107] op_sel_hi:[1,0]
	v_pk_mul_f32 v[76:77], v[76:77], v[106:107] op_sel_hi:[1,0]
	v_pk_mul_f32 v[74:75], v[74:75], v[106:107] op_sel_hi:[1,0]
	v_pk_mul_f32 v[72:73], v[72:73], v[106:107] op_sel_hi:[1,0]
	v_pk_mul_f32 v[70:71], v[70:71], v[106:107] op_sel_hi:[1,0]
	v_pk_mul_f32 v[68:69], v[68:69], v[106:107] op_sel_hi:[1,0]
	v_pk_mul_f32 v[66:67], v[66:67], v[106:107] op_sel_hi:[1,0]
	v_pk_mul_f32 v[64:65], v[64:65], v[106:107] op_sel_hi:[1,0]
	v_pk_mul_f32 v[62:63], v[62:63], v[106:107] op_sel_hi:[1,0]
	v_pk_mul_f32 v[60:61], v[60:61], v[106:107] op_sel_hi:[1,0]
	v_pk_mul_f32 v[58:59], v[58:59], v[106:107] op_sel_hi:[1,0]
	v_pk_mul_f32 v[56:57], v[56:57], v[106:107] op_sel_hi:[1,0]
	v_pk_mul_f32 v[54:55], v[54:55], v[106:107] op_sel_hi:[1,0]
	v_pk_mul_f32 v[52:53], v[52:53], v[106:107] op_sel_hi:[1,0]
	v_pk_mul_f32 v[50:51], v[50:51], v[106:107] op_sel_hi:[1,0]
	v_pk_mul_f32 v[48:49], v[48:49], v[106:107] op_sel_hi:[1,0]
	v_pk_mul_f32 v[46:47], v[46:47], v[106:107] op_sel_hi:[1,0]
	v_pk_mul_f32 v[44:45], v[44:45], v[106:107] op_sel_hi:[1,0]
	v_pk_mul_f32 v[42:43], v[42:43], v[106:107] op_sel_hi:[1,0]
	v_pk_mul_f32 v[40:41], v[40:41], v[106:107] op_sel_hi:[1,0]
	v_pk_mul_f32 v[38:39], v[38:39], v[106:107] op_sel_hi:[1,0]
	v_mul_f32_e32 v166, v166, v106
	s_branch .LBB0_2499
.Lmy_a2B_stub:
	s_mov_b64 s[4:5], s[24:25]
	s_branch .LBB0_2552
.LBB0_2555:
	s_waitcnt vmcnt(0)
	v_mov_b32_e32 v2, v1
	ds_bpermute_b32 v0, v165, v166
	s_nop 0
	v_mbcnt_lo_u32_b32 v2, -1, v2
	v_mbcnt_hi_u32_b32 v4, -1, v2
	v_add_u32_e32 v21, s33, v4
	s_waitcnt lgkmcnt(0)
	v_add_f32_e32 v2, v166, v0
	v_readfirstlane_b32 s12, v21
	s_ashr_i32 s1, s12, 6
	ds_bpermute_b32 v3, v164, v2
	s_lshl_b32 s2, s1, 14
	v_and_b32_e32 v25, 63, v21
	s_add_i32 s2, s2, 0
	s_waitcnt lgkmcnt(0)
	v_lshl_add_u32 v0, v25, 2, s2
	ds_write2st64_b32 v0, v34, v35 offset1:1
	ds_write2st64_b32 v0, v36, v37 offset0:2 offset1:3
	ds_write2st64_b32 v0, v94, v95 offset0:4 offset1:5
	ds_write2st64_b32 v0, v96, v97 offset0:6 offset1:7
	ds_write2st64_b32 v0, v90, v91 offset0:8 offset1:9
	ds_write2st64_b32 v0, v92, v93 offset0:10 offset1:11
	ds_write2st64_b32 v0, v86, v87 offset0:12 offset1:13
	ds_write2st64_b32 v0, v88, v89 offset0:14 offset1:15
	ds_write2st64_b32 v0, v82, v83 offset0:16 offset1:17
	ds_write2st64_b32 v0, v84, v85 offset0:18 offset1:19
	ds_write2st64_b32 v0, v78, v79 offset0:20 offset1:21
	ds_write2st64_b32 v0, v80, v81 offset0:22 offset1:23
	ds_write2st64_b32 v0, v74, v75 offset0:24 offset1:25
	ds_write2st64_b32 v0, v76, v77 offset0:26 offset1:27
	ds_write2st64_b32 v0, v70, v71 offset0:28 offset1:29
	ds_write2st64_b32 v0, v72, v73 offset0:30 offset1:31
	ds_write2st64_b32 v0, v66, v67 offset0:32 offset1:33
	ds_write2st64_b32 v0, v68, v69 offset0:34 offset1:35
	ds_write2st64_b32 v0, v62, v63 offset0:36 offset1:37
	ds_write2st64_b32 v0, v64, v65 offset0:38 offset1:39
	ds_write2st64_b32 v0, v58, v59 offset0:40 offset1:41
	ds_write2st64_b32 v0, v60, v61 offset0:42 offset1:43
	ds_write2st64_b32 v0, v54, v55 offset0:44 offset1:45
	ds_write2st64_b32 v0, v56, v57 offset0:46 offset1:47
	ds_write2st64_b32 v0, v50, v51 offset0:48 offset1:49
	ds_write2st64_b32 v0, v52, v53 offset0:50 offset1:51
	ds_write2st64_b32 v0, v46, v47 offset0:52 offset1:53
	ds_write2st64_b32 v0, v48, v49 offset0:54 offset1:55
	ds_write2st64_b32 v0, v42, v43 offset0:56 offset1:57
	ds_write2st64_b32 v0, v44, v45 offset0:58 offset1:59
	ds_write2st64_b32 v0, v38, v39 offset0:60 offset1:61
	ds_write2st64_b32 v0, v40, v41 offset0:62 offset1:63
	v_and_b32_e32 v0, 15, v21
	v_cmp_gt_u32_e32 vcc, 16, v25
	v_cmp_lt_u32_e64 s[8:9], 15, v25
	v_lshlrev_b32_e32 v30, 3, v0
	s_and_saveexec_b64 s[4:5], s[8:9]
	s_xor_b64 s[4:5], exec, s[4:5]
	v_lshlrev_b32_e32 v4, 3, v0
	s_andn2_saveexec_b64 s[4:5], s[4:5]
	s_cbranch_execz .LBB0_2559
	s_lshl_b32 s2, s1, 7
	s_add_i32 s2, s2, 0
	s_waitcnt lgkmcnt(14)
	v_add_f32_e32 v155, v2, v3
	v_add_u32_e32 v2, s2, v30
	v_add_u32_e32 v2, 0x20000, v2
	v_mov_b32_e32 v4, v30
	ds_write_b64 v2, v[154:155]
